# baseline (speedup 1.0000x reference)
; #define PG8_STAGE(bufoff, gbase, voff) do { _Pragma("unroll") for (int _i = 0; _i < 2; ++_i) \
;         __builtin_amdgcn_global_load_lds((const unsigned*)((const char*)(gbase) + (voff)[_i]), (PG8_LAS unsigned*)(lds + (bufoff) + ldsw + _i * 8192), 16, 0, 0); } while (0)
; #define PG8_LDA(dst, b, h) do { _Pragma("unroll") for (int m = 0; m < 4; ++m) _Pragma("unroll") for (int k = 0; k < 2; ++k) dst[m][k] = *(const PG8_LAS bf16x8*)(lds + PG8_SA(b, h) + aoff + m * 2048 + k * 1024); } while (0)
; #define PG8_LDB(dst, b, h) do { _Pragma("unroll") for (int n = 0; n < 2; ++n) _Pragma("unroll") for (int k = 0; k < 2; ++k) dst[n][k] = *(const PG8_LAS bf16x8*)(lds + PG8_SB(b, h) + boff + n * 2048 + k * 1024); } while (0)
; #define PG8_MMA(ai, bj, At, Bt) do { __builtin_amdgcn_s_setprio(1); _Pragma("unroll") for (int m = 0; m < 4; ++m) _Pragma("unroll") for (int n = 0; n < 2; ++n) _Pragma("unroll") for (int k = 0; k < 2; ++k) \
;         acc[ai][bj][m][n] = __builtin_amdgcn_mfma_f32_16x16x32_bf16(Bt[n][k], At[m][k], acc[ai][bj][m][n], 0, 0, 0); __builtin_amdgcn_s_setprio(0); } while (0)
; #define PG8_WAIT_V(n) asm volatile("s_waitcnt vmcnt(" #n ")" ::: "memory")
; #define PG8_WAIT_L(n) asm volatile("s_waitcnt lgkmcnt(" #n ")" ::: "memory")
; #define PG8_BAR __builtin_amdgcn_s_barrier()
; #define PG8_SCHED __builtin_amdgcn_sched_barrier(0)
; template <class Epi, class Sched, bool ALIGN_EPI = false, bool SP2 = false>
; __device__ __forceinline__ void gemm_phase(PG8_LAS unsigned char* lds, const Gemm g, const Sched& S, const Epi& E, const int wv) {
;     ...
;             const bool last = (t == nt - 2);
;             const char* a1 = cA + (size_t)(t + 1) * kstep;
;             const char* a2 = last ? nA : cA + (size_t)(t + 2) * kstep; const char* b2 = last ? nB : cB + (size_t)(t + 2) * kstep;
;             const char* a3 = a2 + kstep; const char* b3 = b2 + kstep;
;             if (last && has_next) S.a_ready(nxt);
;             if constexpr (SP2) {
;             PG8_LDB(B0, 0, 0); PG8_LDB(B1, 0, 1); PG8_SCHED; PG8_LDA(At, 0, 0); PG8_STAGE(PG8_SA(1, 1), a1 + hstep, voffA);
;             PG8_WAIT_V(8); PG8_WAIT_L(0); PG8_BAR; PG8_MMA(0, 0, At, B0); PG8_MMA(0, 1, At, B1); PG8_BAR; PG8_SCHED;
;             PG8_LDA(At, 0, 1); PG8_STAGE(PG8_SB(0, 0), b2, voffB); PG8_STAGE(PG8_SB(0, 1), b2 + hstep, voffB); PG8_STAGE(PG8_SA(0, 0), a2, voffA);
.LBB0_134:
	s_add_u32 s26, s24, 0xfffc0080
	s_addc_u32 s27, s25, -1
	s_add_i32 s51, 0, 0x10000
	s_cmp_eq_u32 s50, 12
	s_cselect_b32 s29, s17, s27
	s_cselect_b32 s28, s23, s26
	v_add_u32_e32 v0, s51, v183
	s_cselect_b32 s27, s15, s49
	s_cselect_b32 s26, s33, s48
	s_add_i32 s54, 0, 0x14000
	ds_read_b128 v[142:145], v0
	ds_read_b128 v[146:149], v0 offset:1024
	ds_read_b128 v[150:153], v0 offset:2048
	ds_read_b128 v[154:157], v0 offset:3072
	v_add_u32_e32 v0, s54, v183
	ds_read_b128 v[158:161], v0
	ds_read_b128 v[162:165], v0 offset:1024
	ds_read_b128 v[166:169], v0 offset:2048
	ds_read_b128 v[170:173], v0 offset:3072
	v_lshl_add_u64 v[208:209], s[24:25], 0, v[138:139]
	s_add_i32 m0, s39, 0xc000
	ds_read_b128 v[174:177], v186
	ds_read_b128 v[178:181], v186 offset:1024
	ds_read_b128 v[188:191], v186 offset:2048
	ds_read_b128 v[192:195], v186 offset:3072
	ds_read_b128 v[196:199], v186 offset:4096
	ds_read_b128 v[200:203], v186 offset:5120
	ds_read_b128 v[204:207], v186 offset:6144
	ds_read_b128 v[218:221], v186 offset:7168
	global_load_lds_dwordx4 v[208:209], off
	v_lshl_add_u64 v[208:209], s[24:25], 0, v[140:141]
	s_add_i32 m0, s39, 0xe000
	s_nop 0
	global_load_lds_dwordx4 v[208:209], off
	s_waitcnt vmcnt(8)
	s_waitcnt lgkmcnt(0)
	s_setprio 1
	s_barrier
	s_waitcnt lgkmcnt(0)
	v_mfma_f32_16x16x32_bf16 v[126:129], v[142:145], v[174:177], v[126:129]
	v_mfma_f32_16x16x32_bf16 v[122:125], v[150:153], v[174:177], v[122:125]
	v_mfma_f32_16x16x32_bf16 v[110:113], v[142:145], v[188:191], v[110:113]
	v_mfma_f32_16x16x32_bf16 v[106:109], v[150:153], v[188:191], v[106:109]
	v_mfma_f32_16x16x32_bf16 v[94:97], v[142:145], v[196:199], v[94:97]
	v_mfma_f32_16x16x32_bf16 v[90:93], v[150:153], v[196:199], v[90:93]
	v_mfma_f32_16x16x32_bf16 v[78:81], v[142:145], v[204:207], v[78:81]
	v_mfma_f32_16x16x32_bf16 v[74:77], v[150:153], v[204:207], v[74:77]
	v_mfma_f32_16x16x32_bf16 v[126:129], v[146:149], v[178:181], v[126:129]
	v_mfma_f32_16x16x32_bf16 v[122:125], v[154:157], v[178:181], v[122:125]
	v_mfma_f32_16x16x32_bf16 v[110:113], v[146:149], v[192:195], v[110:113]
	v_mfma_f32_16x16x32_bf16 v[106:109], v[154:157], v[192:195], v[106:109]
	v_mfma_f32_16x16x32_bf16 v[94:97], v[146:149], v[200:203], v[94:97]
	v_mfma_f32_16x16x32_bf16 v[90:93], v[154:157], v[200:203], v[90:93]
	v_mfma_f32_16x16x32_bf16 v[78:81], v[146:149], v[218:221], v[78:81]
	v_mfma_f32_16x16x32_bf16 v[74:77], v[154:157], v[218:221], v[74:77]
	s_setprio 0
	s_setprio 1
	v_mfma_f32_16x16x32_bf16 v[118:121], v[158:161], v[174:177], v[118:121]
	v_mfma_f32_16x16x32_bf16 v[114:117], v[166:169], v[174:177], v[114:117]
	v_mfma_f32_16x16x32_bf16 v[102:105], v[158:161], v[188:191], v[102:105]
	v_mfma_f32_16x16x32_bf16 v[98:101], v[166:169], v[188:191], v[98:101]
	v_mfma_f32_16x16x32_bf16 v[86:89], v[158:161], v[196:199], v[86:89]
	v_mfma_f32_16x16x32_bf16 v[82:85], v[166:169], v[196:199], v[82:85]
	v_mfma_f32_16x16x32_bf16 v[70:73], v[158:161], v[204:207], v[70:73]
	v_mfma_f32_16x16x32_bf16 v[66:69], v[166:169], v[204:207], v[66:69]
	v_mfma_f32_16x16x32_bf16 v[118:121], v[162:165], v[178:181], v[118:121]
	v_mfma_f32_16x16x32_bf16 v[114:117], v[170:173], v[178:181], v[114:117]
	v_mfma_f32_16x16x32_bf16 v[102:105], v[162:165], v[192:195], v[102:105]
	v_mfma_f32_16x16x32_bf16 v[98:101], v[170:173], v[192:195], v[98:101]
	v_mfma_f32_16x16x32_bf16 v[86:89], v[162:165], v[200:203], v[86:89]
	v_mfma_f32_16x16x32_bf16 v[82:85], v[170:173], v[200:203], v[82:85]
	v_mfma_f32_16x16x32_bf16 v[70:73], v[162:165], v[218:221], v[70:73]
	v_mfma_f32_16x16x32_bf16 v[66:69], v[170:173], v[218:221], v[66:69]
	s_barrier
	s_setprio 0
	ds_read_b128 v[174:177], v186 offset:16384
	ds_read_b128 v[178:181], v186 offset:17408
	ds_read_b128 v[188:191], v186 offset:18432
	ds_read_b128 v[192:195], v186 offset:19456
	ds_read_b128 v[196:199], v186 offset:20480
	ds_read_b128 v[200:203], v186 offset:21504
	ds_read_b128 v[204:207], v186 offset:22528
	ds_read_b128 v[218:221], v186 offset:23552
	s_add_i32 s51, s51, s35
	v_lshl_add_u64 v[208:209], s[26:27], 0, v[134:135]
	s_mov_b32 m0, s51
	global_load_lds_dwordx4 v[208:209], off
	s_add_i32 m0, s51, 0x2000
	s_add_u32 s52, s26, 0x40000
	v_lshl_add_u64 v[210:211], s[26:27], 0, v[130:131]
	s_addc_u32 s53, s27, 0
	s_add_i32 s51, s54, s35
	global_load_lds_dwordx4 v[210:211], off
	v_lshl_add_u64 v[212:213], s[52:53], 0, v[134:135]
	s_mov_b32 m0, s51
	v_lshl_add_u64 v[214:215], s[28:29], 0, v[132:133]
	global_load_lds_dwordx4 v[212:213], off
	v_lshl_add_u64 v[212:213], s[52:53], 0, v[130:131]
	s_add_i32 m0, s51, 0x2000
	s_nop 0
	global_load_lds_dwordx4 v[212:213], off
	v_lshl_add_u64 v[212:213], s[28:29], 0, v[136:137]
	s_mov_b32 m0, s39
	s_nop 0
	global_load_lds_dwordx4 v[212:213], off
	s_mov_b32 m0, s40
	s_nop 0
	global_load_lds_dwordx4 v[214:215], off
	s_waitcnt vmcnt(8)
	s_waitcnt lgkmcnt(0)
	s_setprio 1
	s_barrier
; #define PG8_STAGE(bufoff, gbase, voff) do { _Pragma("unroll") for (int _i = 0; _i < 2; ++_i) \
;         __builtin_amdgcn_global_load_lds((const unsigned*)((const char*)(gbase) + (voff)[_i]), (PG8_LAS unsigned*)(lds + (bufoff) + ldsw + _i * 8192), 16, 0, 0); } while (0)
; #define PG8_LDA(dst, b, h) do { _Pragma("unroll") for (int m = 0; m < 4; ++m) _Pragma("unroll") for (int k = 0; k < 2; ++k) dst[m][k] = *(const PG8_LAS bf16x8*)(lds + PG8_SA(b, h) + aoff + m * 2048 + k * 1024); } while (0)
; #define PG8_LDB(dst, b, h) do { _Pragma("unroll") for (int n = 0; n < 2; ++n) _Pragma("unroll") for (int k = 0; k < 2; ++k) dst[n][k] = *(const PG8_LAS bf16x8*)(lds + PG8_SB(b, h) + boff + n * 2048 + k * 1024); } while (0)
; #define PG8_MMA(ai, bj, At, Bt) do { __builtin_amdgcn_s_setprio(1); _Pragma("unroll") for (int m = 0; m < 4; ++m) _Pragma("unroll") for (int n = 0; n < 2; ++n) _Pragma("unroll") for (int k = 0; k < 2; ++k) \
;         acc[ai][bj][m][n] = __builtin_amdgcn_mfma_f32_16x16x32_bf16(Bt[n][k], At[m][k], acc[ai][bj][m][n], 0, 0, 0); __builtin_amdgcn_s_setprio(0); } while (0)
; #define PG8_WAIT_V(n) asm volatile("s_waitcnt vmcnt(" #n ")" ::: "memory")
; #define PG8_WAIT_L(n) asm volatile("s_waitcnt lgkmcnt(" #n ")" ::: "memory")
; #define PG8_BAR __builtin_amdgcn_s_barrier()
; #define PG8_SCHED __builtin_amdgcn_sched_barrier(0)
; template <class Epi, class Sched, bool ALIGN_EPI = false, bool SP2 = false>
; __device__ __forceinline__ void gemm_phase(PG8_LAS unsigned char* lds, const Gemm g, const Sched& S, const Epi& E, const int wv) {
;     ...
;             PG8_WAIT_V(8); PG8_WAIT_L(0); PG8_BAR; PG8_MMA(1, 0, At, B0); PG8_MMA(1, 1, At, B1); PG8_BAR; PG8_SCHED;
;             PG8_LDB(B0, 1, 0); PG8_LDB(B1, 1, 1); PG8_SCHED; PG8_LDA(At, 1, 0); PG8_STAGE(PG8_SA(0, 1), a2 + hstep, voffA);
;             PG8_WAIT_V(8); PG8_WAIT_L(0); PG8_BAR; PG8_MMA(0, 0, At, B0); PG8_MMA(0, 1, At, B1); PG8_BAR; PG8_SCHED;
	s_waitcnt lgkmcnt(0)
	v_mfma_f32_16x16x32_bf16 v[62:65], v[142:145], v[174:177], v[62:65]
	v_mfma_f32_16x16x32_bf16 v[58:61], v[150:153], v[174:177], v[58:61]
	v_mfma_f32_16x16x32_bf16 v[46:49], v[142:145], v[188:191], v[46:49]
	v_mfma_f32_16x16x32_bf16 v[42:45], v[150:153], v[188:191], v[42:45]
	v_mfma_f32_16x16x32_bf16 v[30:33], v[142:145], v[196:199], v[30:33]
	v_mfma_f32_16x16x32_bf16 v[26:29], v[150:153], v[196:199], v[26:29]
	v_mfma_f32_16x16x32_bf16 v[14:17], v[142:145], v[204:207], v[14:17]
	v_mfma_f32_16x16x32_bf16 v[10:13], v[150:153], v[204:207], v[10:13]
	v_mfma_f32_16x16x32_bf16 v[62:65], v[146:149], v[178:181], v[62:65]
	v_mfma_f32_16x16x32_bf16 v[58:61], v[154:157], v[178:181], v[58:61]
	v_mfma_f32_16x16x32_bf16 v[46:49], v[146:149], v[192:195], v[46:49]
	v_mfma_f32_16x16x32_bf16 v[42:45], v[154:157], v[192:195], v[42:45]
	v_mfma_f32_16x16x32_bf16 v[30:33], v[146:149], v[200:203], v[30:33]
	v_mfma_f32_16x16x32_bf16 v[26:29], v[154:157], v[200:203], v[26:29]
	v_mfma_f32_16x16x32_bf16 v[14:17], v[146:149], v[218:221], v[14:17]
	v_mfma_f32_16x16x32_bf16 v[10:13], v[154:157], v[218:221], v[10:13]
	s_setprio 0
	s_setprio 1
	v_mfma_f32_16x16x32_bf16 v[54:57], v[158:161], v[174:177], v[54:57]
	v_mfma_f32_16x16x32_bf16 v[50:53], v[166:169], v[174:177], v[50:53]
	v_mfma_f32_16x16x32_bf16 v[38:41], v[158:161], v[188:191], v[38:41]
	v_mfma_f32_16x16x32_bf16 v[34:37], v[166:169], v[188:191], v[34:37]
	v_mfma_f32_16x16x32_bf16 v[22:25], v[158:161], v[196:199], v[22:25]
	v_mfma_f32_16x16x32_bf16 v[18:21], v[166:169], v[196:199], v[18:21]
	v_mfma_f32_16x16x32_bf16 v[6:9], v[158:161], v[204:207], v[6:9]
	v_mfma_f32_16x16x32_bf16 v[2:5], v[166:169], v[204:207], v[2:5]
	v_mfma_f32_16x16x32_bf16 v[54:57], v[162:165], v[178:181], v[54:57]
	v_mfma_f32_16x16x32_bf16 v[50:53], v[170:173], v[178:181], v[50:53]
	v_mfma_f32_16x16x32_bf16 v[38:41], v[162:165], v[192:195], v[38:41]
	v_mfma_f32_16x16x32_bf16 v[34:37], v[170:173], v[192:195], v[34:37]
	v_mfma_f32_16x16x32_bf16 v[22:25], v[162:165], v[200:203], v[22:25]
	v_mfma_f32_16x16x32_bf16 v[18:21], v[170:173], v[200:203], v[18:21]
	v_mfma_f32_16x16x32_bf16 v[6:9], v[162:165], v[218:221], v[6:9]
	v_mfma_f32_16x16x32_bf16 v[2:5], v[170:173], v[218:221], v[2:5]
	s_barrier
	s_setprio 0
	s_add_i32 s51, 0, 0x18000
	v_add_u32_e32 v0, s51, v183
	s_add_i32 s52, 0, 0x1c000
	ds_read_b128 v[142:145], v0
	ds_read_b128 v[146:149], v0 offset:1024
	ds_read_b128 v[150:153], v0 offset:2048
	ds_read_b128 v[154:157], v0 offset:3072
	v_add_u32_e32 v0, s52, v183
	ds_read_b128 v[158:161], v0
	ds_read_b128 v[162:165], v0 offset:1024
	ds_read_b128 v[166:169], v0 offset:2048
	ds_read_b128 v[170:173], v0 offset:3072
	s_add_u32 s28, s28, 0x40000
	s_addc_u32 s29, s29, 0
	s_mov_b32 m0, s41
	v_lshl_add_u64 v[216:217], s[28:29], 0, v[136:137]
	ds_read_b128 v[174:177], v186 offset:32768
	ds_read_b128 v[178:181], v186 offset:33792
	ds_read_b128 v[188:191], v186 offset:34816
	ds_read_b128 v[192:195], v186 offset:35840
	ds_read_b128 v[196:199], v186 offset:36864
	ds_read_b128 v[200:203], v186 offset:37888
	ds_read_b128 v[204:207], v186 offset:38912
	ds_read_b128 v[218:221], v186 offset:39936
	global_load_lds_dwordx4 v[216:217], off
	v_lshl_add_u64 v[216:217], s[28:29], 0, v[132:133]
	s_mov_b32 m0, s42
	s_nop 0
	global_load_lds_dwordx4 v[216:217], off
	s_waitcnt vmcnt(8)
	s_waitcnt lgkmcnt(0)
	s_setprio 1
	s_barrier
	s_waitcnt lgkmcnt(0)
	v_mfma_f32_16x16x32_bf16 v[126:129], v[142:145], v[174:177], v[126:129]
	v_mfma_f32_16x16x32_bf16 v[122:125], v[150:153], v[174:177], v[122:125]
	v_mfma_f32_16x16x32_bf16 v[110:113], v[142:145], v[188:191], v[110:113]
	v_mfma_f32_16x16x32_bf16 v[106:109], v[150:153], v[188:191], v[106:109]
	v_mfma_f32_16x16x32_bf16 v[94:97], v[142:145], v[196:199], v[94:97]
	v_mfma_f32_16x16x32_bf16 v[90:93], v[150:153], v[196:199], v[90:93]
	v_mfma_f32_16x16x32_bf16 v[78:81], v[142:145], v[204:207], v[78:81]
	v_mfma_f32_16x16x32_bf16 v[74:77], v[150:153], v[204:207], v[74:77]
	v_mfma_f32_16x16x32_bf16 v[126:129], v[146:149], v[178:181], v[126:129]
	v_mfma_f32_16x16x32_bf16 v[122:125], v[154:157], v[178:181], v[122:125]
	v_mfma_f32_16x16x32_bf16 v[110:113], v[146:149], v[192:195], v[110:113]
	v_mfma_f32_16x16x32_bf16 v[106:109], v[154:157], v[192:195], v[106:109]
	v_mfma_f32_16x16x32_bf16 v[94:97], v[146:149], v[200:203], v[94:97]
	v_mfma_f32_16x16x32_bf16 v[90:93], v[154:157], v[200:203], v[90:93]
	v_mfma_f32_16x16x32_bf16 v[78:81], v[146:149], v[218:221], v[78:81]
	v_mfma_f32_16x16x32_bf16 v[74:77], v[154:157], v[218:221], v[74:77]
	s_setprio 0
	s_setprio 1
	v_mfma_f32_16x16x32_bf16 v[118:121], v[158:161], v[174:177], v[118:121]
	v_mfma_f32_16x16x32_bf16 v[114:117], v[166:169], v[174:177], v[114:117]
	v_mfma_f32_16x16x32_bf16 v[102:105], v[158:161], v[188:191], v[102:105]
	v_mfma_f32_16x16x32_bf16 v[98:101], v[166:169], v[188:191], v[98:101]
	v_mfma_f32_16x16x32_bf16 v[86:89], v[158:161], v[196:199], v[86:89]
	v_mfma_f32_16x16x32_bf16 v[82:85], v[166:169], v[196:199], v[82:85]
	v_mfma_f32_16x16x32_bf16 v[70:73], v[158:161], v[204:207], v[70:73]
	v_mfma_f32_16x16x32_bf16 v[66:69], v[166:169], v[204:207], v[66:69]
	v_mfma_f32_16x16x32_bf16 v[118:121], v[162:165], v[178:181], v[118:121]
	v_mfma_f32_16x16x32_bf16 v[114:117], v[170:173], v[178:181], v[114:117]
	v_mfma_f32_16x16x32_bf16 v[102:105], v[162:165], v[192:195], v[102:105]
	v_mfma_f32_16x16x32_bf16 v[98:101], v[170:173], v[192:195], v[98:101]
	v_mfma_f32_16x16x32_bf16 v[86:89], v[162:165], v[200:203], v[86:89]
	v_mfma_f32_16x16x32_bf16 v[82:85], v[170:173], v[200:203], v[82:85]
	v_mfma_f32_16x16x32_bf16 v[70:73], v[162:165], v[218:221], v[70:73]
	v_mfma_f32_16x16x32_bf16 v[66:69], v[170:173], v[218:221], v[66:69]
	s_barrier
; #define PG8_STAGE(bufoff, gbase, voff) do { _Pragma("unroll") for (int _i = 0; _i < 2; ++_i) \
;         __builtin_amdgcn_global_load_lds((const unsigned*)((const char*)(gbase) + (voff)[_i]), (PG8_LAS unsigned*)(lds + (bufoff) + ldsw + _i * 8192), 16, 0, 0); } while (0)
; #define PG8_LDA(dst, b, h) do { _Pragma("unroll") for (int m = 0; m < 4; ++m) _Pragma("unroll") for (int k = 0; k < 2; ++k) dst[m][k] = *(const PG8_LAS bf16x8*)(lds + PG8_SA(b, h) + aoff + m * 2048 + k * 1024); } while (0)
; #define PG8_MMA(ai, bj, At, Bt) do { __builtin_amdgcn_s_setprio(1); _Pragma("unroll") for (int m = 0; m < 4; ++m) _Pragma("unroll") for (int n = 0; n < 2; ++n) _Pragma("unroll") for (int k = 0; k < 2; ++k) \
;         acc[ai][bj][m][n] = __builtin_amdgcn_mfma_f32_16x16x32_bf16(Bt[n][k], At[m][k], acc[ai][bj][m][n], 0, 0, 0); __builtin_amdgcn_s_setprio(0); } while (0)
; #define PG8_WAIT_V(n) asm volatile("s_waitcnt vmcnt(" #n ")" ::: "memory")
; #define PG8_WAIT_L(n) asm volatile("s_waitcnt lgkmcnt(" #n ")" ::: "memory")
; #define PG8_BAR __builtin_amdgcn_s_barrier()
; #define PG8_SCHED __builtin_amdgcn_sched_barrier(0)
; template <class Epi, class Sched, bool ALIGN_EPI = false, bool SP2 = false>
; __device__ __forceinline__ void gemm_phase(PG8_LAS unsigned char* lds, const Gemm g, const Sched& S, const Epi& E, const int wv) {
;     ...
;             PG8_LDA(At, 1, 1); PG8_STAGE(PG8_SB(1, 0), b3, voffB); PG8_STAGE(PG8_SB(1, 1), b3 + hstep, voffB); PG8_STAGE(PG8_SA(1, 0), a3, voffA);
;             PG8_WAIT_V(8); PG8_WAIT_L(0); PG8_BAR; PG8_MMA(1, 0, At, B0); PG8_MMA(1, 1, At, B1); PG8_BAR; PG8_SCHED;
	s_setprio 0
	ds_read_b128 v[174:177], v186 offset:49152
	ds_read_b128 v[178:181], v186 offset:50176
	ds_read_b128 v[188:191], v186 offset:51200
	ds_read_b128 v[192:195], v186 offset:52224
	ds_read_b128 v[196:199], v186 offset:53248
	ds_read_b128 v[200:203], v186 offset:54272
	ds_read_b128 v[204:207], v186 offset:55296
	ds_read_b128 v[218:221], v186 offset:56320
	s_add_i32 s28, s51, s35
	v_lshl_add_u64 v[208:209], v[208:209], 0, s[2:3]
	s_mov_b32 m0, s28
	global_load_lds_dwordx4 v[208:209], off
	s_add_i32 m0, s28, 0x2000
	s_add_u32 s26, s26, 0x40080
	v_lshl_add_u64 v[208:209], v[210:211], 0, s[2:3]
	s_addc_u32 s27, s27, 0
	s_add_i32 s28, s52, s35
	global_load_lds_dwordx4 v[208:209], off
	v_lshl_add_u64 v[208:209], s[26:27], 0, v[134:135]
	s_mov_b32 m0, s28
	s_nop 0
	global_load_lds_dwordx4 v[208:209], off
	v_lshl_add_u64 v[208:209], s[26:27], 0, v[130:131]
	s_add_i32 m0, s28, 0x2000
	s_nop 0
	global_load_lds_dwordx4 v[208:209], off
	v_lshl_add_u64 v[208:209], v[212:213], 0, s[2:3]
	s_mov_b32 m0, s44
	s_nop 0
	global_load_lds_dwordx4 v[208:209], off
	v_lshl_add_u64 v[208:209], v[214:215], 0, s[2:3]
	s_mov_b32 m0, s45
	s_nop 0
	global_load_lds_dwordx4 v[208:209], off
	s_waitcnt vmcnt(8)
	s_waitcnt lgkmcnt(0)
	s_setprio 1
	s_barrier
	s_waitcnt lgkmcnt(0)
	v_mfma_f32_16x16x32_bf16 v[62:65], v[142:145], v[174:177], v[62:65]
	v_mfma_f32_16x16x32_bf16 v[58:61], v[150:153], v[174:177], v[58:61]
	v_mfma_f32_16x16x32_bf16 v[46:49], v[142:145], v[188:191], v[46:49]
	v_mfma_f32_16x16x32_bf16 v[42:45], v[150:153], v[188:191], v[42:45]
	v_mfma_f32_16x16x32_bf16 v[30:33], v[142:145], v[196:199], v[30:33]
	v_mfma_f32_16x16x32_bf16 v[26:29], v[150:153], v[196:199], v[26:29]
	v_mfma_f32_16x16x32_bf16 v[14:17], v[142:145], v[204:207], v[14:17]
	v_mfma_f32_16x16x32_bf16 v[10:13], v[150:153], v[204:207], v[10:13]
	v_mfma_f32_16x16x32_bf16 v[62:65], v[146:149], v[178:181], v[62:65]
	v_mfma_f32_16x16x32_bf16 v[58:61], v[154:157], v[178:181], v[58:61]
	v_mfma_f32_16x16x32_bf16 v[46:49], v[146:149], v[192:195], v[46:49]
	v_mfma_f32_16x16x32_bf16 v[42:45], v[154:157], v[192:195], v[42:45]
	v_mfma_f32_16x16x32_bf16 v[30:33], v[146:149], v[200:203], v[30:33]
	v_mfma_f32_16x16x32_bf16 v[26:29], v[154:157], v[200:203], v[26:29]
	v_mfma_f32_16x16x32_bf16 v[14:17], v[146:149], v[218:221], v[14:17]
	v_mfma_f32_16x16x32_bf16 v[10:13], v[154:157], v[218:221], v[10:13]
	s_setprio 0
	s_setprio 1
	v_mfma_f32_16x16x32_bf16 v[54:57], v[158:161], v[174:177], v[54:57]
	v_mfma_f32_16x16x32_bf16 v[50:53], v[166:169], v[174:177], v[50:53]
	v_mfma_f32_16x16x32_bf16 v[38:41], v[158:161], v[188:191], v[38:41]
	v_mfma_f32_16x16x32_bf16 v[34:37], v[166:169], v[188:191], v[34:37]
	v_mfma_f32_16x16x32_bf16 v[22:25], v[158:161], v[196:199], v[22:25]
	v_mfma_f32_16x16x32_bf16 v[18:21], v[166:169], v[196:199], v[18:21]
	v_mfma_f32_16x16x32_bf16 v[6:9], v[158:161], v[204:207], v[6:9]
	v_mfma_f32_16x16x32_bf16 v[2:5], v[166:169], v[204:207], v[2:5]
	v_mfma_f32_16x16x32_bf16 v[54:57], v[162:165], v[178:181], v[54:57]
	v_mfma_f32_16x16x32_bf16 v[50:53], v[170:173], v[178:181], v[50:53]
	v_mfma_f32_16x16x32_bf16 v[38:41], v[162:165], v[192:195], v[38:41]
	v_mfma_f32_16x16x32_bf16 v[34:37], v[170:173], v[192:195], v[34:37]
	v_mfma_f32_16x16x32_bf16 v[22:25], v[162:165], v[200:203], v[22:25]
	v_mfma_f32_16x16x32_bf16 v[18:21], v[170:173], v[200:203], v[18:21]
	v_mfma_f32_16x16x32_bf16 v[6:9], v[162:165], v[218:221], v[6:9]
	v_mfma_f32_16x16x32_bf16 v[2:5], v[170:173], v[218:221], v[2:5]
	s_barrier
	s_setprio 0
	s_add_i32 s50, s50, 2
	s_add_u32 s24, s24, 0x100
	s_addc_u32 s25, s25, 0
	s_add_u32 s48, s48, 0x100
	s_addc_u32 s49, s49, 0
	s_cmp_gt_u32 s50, 13
	s_cbranch_scc0 .LBB0_134
	s_and_b64 vcc, exec, s[10:11]
	s_cbranch_vccz .LBB0_137
	s_barrier

; #define PG8_STAGE(bufoff, gbase, voff) do { _Pragma("unroll") for (int _i = 0; _i < 2; ++_i) \
;         __builtin_amdgcn_global_load_lds((const unsigned*)((const char*)(gbase) + (voff)[_i]), (PG8_LAS unsigned*)(lds + (bufoff) + ldsw + _i * 8192), 16, 0, 0); } while (0)
; #define PG8_LDA(dst, b, h) do { _Pragma("unroll") for (int m = 0; m < 4; ++m) _Pragma("unroll") for (int k = 0; k < 2; ++k) dst[m][k] = *(const PG8_LAS bf16x8*)(lds + PG8_SA(b, h) + aoff + m * 2048 + k * 1024); } while (0)
; #define PG8_LDB(dst, b, h) do { _Pragma("unroll") for (int n = 0; n < 2; ++n) _Pragma("unroll") for (int k = 0; k < 2; ++k) dst[n][k] = *(const PG8_LAS bf16x8*)(lds + PG8_SB(b, h) + boff + n * 2048 + k * 1024); } while (0)
; #define PG8_MMA(ai, bj, At, Bt) do { __builtin_amdgcn_s_setprio(1); _Pragma("unroll") for (int m = 0; m < 4; ++m) _Pragma("unroll") for (int n = 0; n < 2; ++n) _Pragma("unroll") for (int k = 0; k < 2; ++k) \
;         acc[ai][bj][m][n] = __builtin_amdgcn_mfma_f32_16x16x32_bf16(Bt[n][k], At[m][k], acc[ai][bj][m][n], 0, 0, 0); __builtin_amdgcn_s_setprio(0); } while (0)
; #define PG8_WAIT_V(n) asm volatile("s_waitcnt vmcnt(" #n ")" ::: "memory")
; #define PG8_WAIT_L(n) asm volatile("s_waitcnt lgkmcnt(" #n ")" ::: "memory")
; #define PG8_BAR __builtin_amdgcn_s_barrier()
; #define PG8_SCHED __builtin_amdgcn_sched_barrier(0)
; template <class Epi, class Sched, bool ALIGN_EPI = false, bool SP2 = false>
; __device__ __forceinline__ void gemm_phase(PG8_LAS unsigned char* lds, const Gemm g, const Sched& S, const Epi& E, const int wv) {
;     ...
;             const bool last = (t == nt - 2);
;             const char* a1 = cA + (size_t)(t + 1) * kstep;
;             const char* a2 = last ? nA : cA + (size_t)(t + 2) * kstep; const char* b2 = last ? nB : cB + (size_t)(t + 2) * kstep;
;             const char* a3 = a2 + kstep; const char* b3 = b2 + kstep;
;             if (last && has_next) S.a_ready(nxt);
;             if constexpr (SP2) {
;             PG8_LDB(B0, 0, 0); PG8_LDB(B1, 0, 1); PG8_SCHED; PG8_LDA(At, 0, 0); PG8_STAGE(PG8_SA(1, 1), a1 + hstep, voffA);
;             PG8_WAIT_V(8); PG8_WAIT_L(0); PG8_BAR; PG8_MMA(0, 0, At, B0); PG8_MMA(0, 1, At, B1); PG8_BAR; PG8_SCHED;
;             PG8_LDA(At, 0, 1); PG8_STAGE(PG8_SB(0, 0), b2, voffB); PG8_STAGE(PG8_SB(0, 1), b2 + hstep, voffB); PG8_STAGE(PG8_SA(0, 0), a2, voffA);
.LBB0_156:
	s_add_u32 s20, s18, 0xfffc0080
	s_addc_u32 s21, s19, -1
	s_add_i32 s45, 0, 0x10000
	s_cmp_eq_u32 s44, 12
	s_cselect_b32 s23, s11, s21
	s_cselect_b32 s22, s40, s20
	v_add_u32_e32 v152, s45, v155
	s_cselect_b32 s21, s9, s43
	s_cselect_b32 s20, s41, s42
	s_add_i32 s48, 0, 0x14000
	ds_read_b128 v[140:143], v152
	ds_read_b128 v[144:147], v152 offset:1024
	ds_read_b128 v[148:151], v152 offset:2048
	ds_read_b128 v[158:161], v152 offset:3072
	v_add_u32_e32 v152, s48, v155
	ds_read_b128 v[162:165], v152
	ds_read_b128 v[166:169], v152 offset:1024
	ds_read_b128 v[170:173], v152 offset:2048
	ds_read_b128 v[174:177], v152 offset:3072
	v_lshl_add_u64 v[152:153], s[18:19], 0, v[136:137]
	s_add_i32 m0, s17, 0xc000
	ds_read_b128 v[178:181], v157
	ds_read_b128 v[182:185], v157 offset:1024
	ds_read_b128 v[186:189], v157 offset:2048
	ds_read_b128 v[190:193], v157 offset:3072
	ds_read_b128 v[194:197], v157 offset:4096
	ds_read_b128 v[198:201], v157 offset:5120
	ds_read_b128 v[202:205], v157 offset:6144
	ds_read_b128 v[206:209], v157 offset:7168
	global_load_lds_dwordx4 v[152:153], off
	v_lshl_add_u64 v[152:153], s[18:19], 0, v[138:139]
	s_add_i32 m0, s17, 0xe000
	s_nop 0
	global_load_lds_dwordx4 v[152:153], off
	s_waitcnt vmcnt(8)
	s_waitcnt lgkmcnt(0)
	s_setprio 1
	s_barrier
	s_waitcnt lgkmcnt(0)
	v_mfma_f32_16x16x32_bf16 v[126:129], v[140:143], v[178:181], v[126:129]
	v_mfma_f32_16x16x32_bf16 v[122:125], v[148:151], v[178:181], v[122:125]
	v_mfma_f32_16x16x32_bf16 v[118:121], v[140:143], v[186:189], v[118:121]
	v_mfma_f32_16x16x32_bf16 v[114:117], v[148:151], v[186:189], v[114:117]
	v_mfma_f32_16x16x32_bf16 v[98:101], v[140:143], v[194:197], v[98:101]
	v_mfma_f32_16x16x32_bf16 v[90:93], v[148:151], v[194:197], v[90:93]
	v_mfma_f32_16x16x32_bf16 v[78:81], v[140:143], v[202:205], v[78:81]
	v_mfma_f32_16x16x32_bf16 v[74:77], v[148:151], v[202:205], v[74:77]
	v_mfma_f32_16x16x32_bf16 v[126:129], v[144:147], v[182:185], v[126:129]
	v_mfma_f32_16x16x32_bf16 v[122:125], v[158:161], v[182:185], v[122:125]
	v_mfma_f32_16x16x32_bf16 v[118:121], v[144:147], v[190:193], v[118:121]
	v_mfma_f32_16x16x32_bf16 v[114:117], v[158:161], v[190:193], v[114:117]
	v_mfma_f32_16x16x32_bf16 v[98:101], v[144:147], v[198:201], v[98:101]
	v_mfma_f32_16x16x32_bf16 v[90:93], v[158:161], v[198:201], v[90:93]
	v_mfma_f32_16x16x32_bf16 v[78:81], v[144:147], v[206:209], v[78:81]
	v_mfma_f32_16x16x32_bf16 v[74:77], v[158:161], v[206:209], v[74:77]
	s_setprio 0
	s_setprio 1
	v_mfma_f32_16x16x32_bf16 v[110:113], v[162:165], v[178:181], v[110:113]
	v_mfma_f32_16x16x32_bf16 v[106:109], v[170:173], v[178:181], v[106:109]
	v_mfma_f32_16x16x32_bf16 v[102:105], v[162:165], v[186:189], v[102:105]
	v_mfma_f32_16x16x32_bf16 v[94:97], v[170:173], v[186:189], v[94:97]
	v_mfma_f32_16x16x32_bf16 v[86:89], v[162:165], v[194:197], v[86:89]
	v_mfma_f32_16x16x32_bf16 v[82:85], v[170:173], v[194:197], v[82:85]
	v_mfma_f32_16x16x32_bf16 v[70:73], v[162:165], v[202:205], v[70:73]
	v_mfma_f32_16x16x32_bf16 v[66:69], v[170:173], v[202:205], v[66:69]
	v_mfma_f32_16x16x32_bf16 v[110:113], v[166:169], v[182:185], v[110:113]
	v_mfma_f32_16x16x32_bf16 v[106:109], v[174:177], v[182:185], v[106:109]
	v_mfma_f32_16x16x32_bf16 v[102:105], v[166:169], v[190:193], v[102:105]
	v_mfma_f32_16x16x32_bf16 v[94:97], v[174:177], v[190:193], v[94:97]
	v_mfma_f32_16x16x32_bf16 v[86:89], v[166:169], v[198:201], v[86:89]
	v_mfma_f32_16x16x32_bf16 v[82:85], v[174:177], v[198:201], v[82:85]
	v_mfma_f32_16x16x32_bf16 v[70:73], v[166:169], v[206:209], v[70:73]
	v_mfma_f32_16x16x32_bf16 v[66:69], v[174:177], v[206:209], v[66:69]
	s_barrier
	s_setprio 0
	ds_read_b128 v[178:181], v157 offset:16384
	ds_read_b128 v[182:185], v157 offset:17408
	ds_read_b128 v[186:189], v157 offset:18432
	ds_read_b128 v[190:193], v157 offset:19456
	ds_read_b128 v[194:197], v157 offset:20480
	ds_read_b128 v[198:201], v157 offset:21504
	ds_read_b128 v[202:205], v157 offset:22528
	ds_read_b128 v[206:209], v157 offset:23552
	s_add_i32 s45, s45, s24
	v_lshl_add_u64 v[152:153], s[20:21], 0, v[0:1]
	s_mov_b32 m0, s45
	global_load_lds_dwordx4 v[152:153], off
	s_add_i32 m0, s45, 0x2000
	s_add_u32 s46, s20, 0x40000
	v_lshl_add_u64 v[210:211], s[20:21], 0, v[130:131]
	s_addc_u32 s47, s21, 0
	s_add_i32 s45, s48, s24
	global_load_lds_dwordx4 v[210:211], off
	v_lshl_add_u64 v[212:213], s[46:47], 0, v[0:1]
	s_mov_b32 m0, s45
	v_lshl_add_u64 v[214:215], s[22:23], 0, v[132:133]
	global_load_lds_dwordx4 v[212:213], off
	v_lshl_add_u64 v[212:213], s[46:47], 0, v[130:131]
	s_add_i32 m0, s45, 0x2000
	s_nop 0
	global_load_lds_dwordx4 v[212:213], off
	v_lshl_add_u64 v[212:213], s[22:23], 0, v[134:135]
	s_mov_b32 m0, s17
	s_nop 0
	global_load_lds_dwordx4 v[212:213], off
	s_mov_b32 m0, s26
	s_nop 0
	global_load_lds_dwordx4 v[214:215], off
	s_waitcnt vmcnt(8)
	s_waitcnt lgkmcnt(0)
	s_setprio 1
	s_barrier
; #define PG8_STAGE(bufoff, gbase, voff) do { _Pragma("unroll") for (int _i = 0; _i < 2; ++_i) \
;         __builtin_amdgcn_global_load_lds((const unsigned*)((const char*)(gbase) + (voff)[_i]), (PG8_LAS unsigned*)(lds + (bufoff) + ldsw + _i * 8192), 16, 0, 0); } while (0)
; #define PG8_LDA(dst, b, h) do { _Pragma("unroll") for (int m = 0; m < 4; ++m) _Pragma("unroll") for (int k = 0; k < 2; ++k) dst[m][k] = *(const PG8_LAS bf16x8*)(lds + PG8_SA(b, h) + aoff + m * 2048 + k * 1024); } while (0)
; #define PG8_LDB(dst, b, h) do { _Pragma("unroll") for (int n = 0; n < 2; ++n) _Pragma("unroll") for (int k = 0; k < 2; ++k) dst[n][k] = *(const PG8_LAS bf16x8*)(lds + PG8_SB(b, h) + boff + n * 2048 + k * 1024); } while (0)
; #define PG8_MMA(ai, bj, At, Bt) do { __builtin_amdgcn_s_setprio(1); _Pragma("unroll") for (int m = 0; m < 4; ++m) _Pragma("unroll") for (int n = 0; n < 2; ++n) _Pragma("unroll") for (int k = 0; k < 2; ++k) \
;         acc[ai][bj][m][n] = __builtin_amdgcn_mfma_f32_16x16x32_bf16(Bt[n][k], At[m][k], acc[ai][bj][m][n], 0, 0, 0); __builtin_amdgcn_s_setprio(0); } while (0)
; #define PG8_WAIT_V(n) asm volatile("s_waitcnt vmcnt(" #n ")" ::: "memory")
; #define PG8_WAIT_L(n) asm volatile("s_waitcnt lgkmcnt(" #n ")" ::: "memory")
; #define PG8_BAR __builtin_amdgcn_s_barrier()
; #define PG8_SCHED __builtin_amdgcn_sched_barrier(0)
; template <class Epi, class Sched, bool ALIGN_EPI = false, bool SP2 = false>
; __device__ __forceinline__ void gemm_phase(PG8_LAS unsigned char* lds, const Gemm g, const Sched& S, const Epi& E, const int wv) {
;     ...
;             PG8_WAIT_V(8); PG8_WAIT_L(0); PG8_BAR; PG8_MMA(1, 0, At, B0); PG8_MMA(1, 1, At, B1); PG8_BAR; PG8_SCHED;
;             PG8_LDB(B0, 1, 0); PG8_LDB(B1, 1, 1); PG8_SCHED; PG8_LDA(At, 1, 0); PG8_STAGE(PG8_SA(0, 1), a2 + hstep, voffA);
;             PG8_WAIT_V(8); PG8_WAIT_L(0); PG8_BAR; PG8_MMA(0, 0, At, B0); PG8_MMA(0, 1, At, B1); PG8_BAR; PG8_SCHED;
	s_waitcnt lgkmcnt(0)
	v_mfma_f32_16x16x32_bf16 v[62:65], v[140:143], v[178:181], v[62:65]
	v_mfma_f32_16x16x32_bf16 v[58:61], v[148:151], v[178:181], v[58:61]
	v_mfma_f32_16x16x32_bf16 v[46:49], v[140:143], v[186:189], v[46:49]
	v_mfma_f32_16x16x32_bf16 v[42:45], v[148:151], v[186:189], v[42:45]
	v_mfma_f32_16x16x32_bf16 v[30:33], v[140:143], v[194:197], v[30:33]
	v_mfma_f32_16x16x32_bf16 v[26:29], v[148:151], v[194:197], v[26:29]
	v_mfma_f32_16x16x32_bf16 v[14:17], v[140:143], v[202:205], v[14:17]
	v_mfma_f32_16x16x32_bf16 v[10:13], v[148:151], v[202:205], v[10:13]
	v_mfma_f32_16x16x32_bf16 v[62:65], v[144:147], v[182:185], v[62:65]
	v_mfma_f32_16x16x32_bf16 v[58:61], v[158:161], v[182:185], v[58:61]
	v_mfma_f32_16x16x32_bf16 v[46:49], v[144:147], v[190:193], v[46:49]
	v_mfma_f32_16x16x32_bf16 v[42:45], v[158:161], v[190:193], v[42:45]
	v_mfma_f32_16x16x32_bf16 v[30:33], v[144:147], v[198:201], v[30:33]
	v_mfma_f32_16x16x32_bf16 v[26:29], v[158:161], v[198:201], v[26:29]
	v_mfma_f32_16x16x32_bf16 v[14:17], v[144:147], v[206:209], v[14:17]
	v_mfma_f32_16x16x32_bf16 v[10:13], v[158:161], v[206:209], v[10:13]
	s_setprio 0
	s_setprio 1
	v_mfma_f32_16x16x32_bf16 v[54:57], v[162:165], v[178:181], v[54:57]
	v_mfma_f32_16x16x32_bf16 v[50:53], v[170:173], v[178:181], v[50:53]
	v_mfma_f32_16x16x32_bf16 v[38:41], v[162:165], v[186:189], v[38:41]
	v_mfma_f32_16x16x32_bf16 v[34:37], v[170:173], v[186:189], v[34:37]
	v_mfma_f32_16x16x32_bf16 v[22:25], v[162:165], v[194:197], v[22:25]
	v_mfma_f32_16x16x32_bf16 v[18:21], v[170:173], v[194:197], v[18:21]
	v_mfma_f32_16x16x32_bf16 v[6:9], v[162:165], v[202:205], v[6:9]
	v_mfma_f32_16x16x32_bf16 v[2:5], v[170:173], v[202:205], v[2:5]
	v_mfma_f32_16x16x32_bf16 v[54:57], v[166:169], v[182:185], v[54:57]
	v_mfma_f32_16x16x32_bf16 v[50:53], v[174:177], v[182:185], v[50:53]
	v_mfma_f32_16x16x32_bf16 v[38:41], v[166:169], v[190:193], v[38:41]
	v_mfma_f32_16x16x32_bf16 v[34:37], v[174:177], v[190:193], v[34:37]
	v_mfma_f32_16x16x32_bf16 v[22:25], v[166:169], v[198:201], v[22:25]
	v_mfma_f32_16x16x32_bf16 v[18:21], v[174:177], v[198:201], v[18:21]
	v_mfma_f32_16x16x32_bf16 v[6:9], v[166:169], v[206:209], v[6:9]
	v_mfma_f32_16x16x32_bf16 v[2:5], v[174:177], v[206:209], v[2:5]
	s_barrier
	s_setprio 0
	s_add_i32 s45, 0, 0x18000
	s_add_i32 s46, 0, 0x1c000
	v_add_u32_e32 v158, s45, v155
	v_add_u32_e32 v174, s46, v155
	ds_read_b128 v[140:143], v158
	ds_read_b128 v[144:147], v158 offset:1024
	ds_read_b128 v[148:151], v158 offset:2048
	ds_read_b128 v[158:161], v158 offset:3072
	ds_read_b128 v[162:165], v174
	ds_read_b128 v[166:169], v174 offset:1024
	ds_read_b128 v[170:173], v174 offset:2048
	ds_read_b128 v[174:177], v174 offset:3072
	s_add_u32 s22, s22, 0x40000
	s_addc_u32 s23, s23, 0
	s_mov_b32 m0, s27
	v_lshl_add_u64 v[216:217], s[22:23], 0, v[134:135]
	ds_read_b128 v[178:181], v157 offset:32768
	ds_read_b128 v[182:185], v157 offset:33792
	ds_read_b128 v[186:189], v157 offset:34816
	ds_read_b128 v[190:193], v157 offset:35840
	ds_read_b128 v[194:197], v157 offset:36864
	ds_read_b128 v[198:201], v157 offset:37888
	ds_read_b128 v[202:205], v157 offset:38912
	ds_read_b128 v[206:209], v157 offset:39936
	global_load_lds_dwordx4 v[216:217], off
	v_lshl_add_u64 v[216:217], s[22:23], 0, v[132:133]
	s_mov_b32 m0, s28
	s_nop 0
	global_load_lds_dwordx4 v[216:217], off
	s_waitcnt vmcnt(8)
	s_waitcnt lgkmcnt(0)
	s_setprio 1
	s_barrier
	s_waitcnt lgkmcnt(0)
	v_mfma_f32_16x16x32_bf16 v[126:129], v[140:143], v[178:181], v[126:129]
	v_mfma_f32_16x16x32_bf16 v[122:125], v[148:151], v[178:181], v[122:125]
	v_mfma_f32_16x16x32_bf16 v[118:121], v[140:143], v[186:189], v[118:121]
	v_mfma_f32_16x16x32_bf16 v[114:117], v[148:151], v[186:189], v[114:117]
	v_mfma_f32_16x16x32_bf16 v[98:101], v[140:143], v[194:197], v[98:101]
	v_mfma_f32_16x16x32_bf16 v[90:93], v[148:151], v[194:197], v[90:93]
	v_mfma_f32_16x16x32_bf16 v[78:81], v[140:143], v[202:205], v[78:81]
	v_mfma_f32_16x16x32_bf16 v[74:77], v[148:151], v[202:205], v[74:77]
	v_mfma_f32_16x16x32_bf16 v[126:129], v[144:147], v[182:185], v[126:129]
	v_mfma_f32_16x16x32_bf16 v[122:125], v[158:161], v[182:185], v[122:125]
	v_mfma_f32_16x16x32_bf16 v[118:121], v[144:147], v[190:193], v[118:121]
	v_mfma_f32_16x16x32_bf16 v[114:117], v[158:161], v[190:193], v[114:117]
	v_mfma_f32_16x16x32_bf16 v[98:101], v[144:147], v[198:201], v[98:101]
	v_mfma_f32_16x16x32_bf16 v[90:93], v[158:161], v[198:201], v[90:93]
	v_mfma_f32_16x16x32_bf16 v[78:81], v[144:147], v[206:209], v[78:81]
	v_mfma_f32_16x16x32_bf16 v[74:77], v[158:161], v[206:209], v[74:77]
	s_setprio 0
	s_setprio 1
	v_mfma_f32_16x16x32_bf16 v[110:113], v[162:165], v[178:181], v[110:113]
	v_mfma_f32_16x16x32_bf16 v[106:109], v[170:173], v[178:181], v[106:109]
	v_mfma_f32_16x16x32_bf16 v[102:105], v[162:165], v[186:189], v[102:105]
	v_mfma_f32_16x16x32_bf16 v[94:97], v[170:173], v[186:189], v[94:97]
	v_mfma_f32_16x16x32_bf16 v[86:89], v[162:165], v[194:197], v[86:89]
	v_mfma_f32_16x16x32_bf16 v[82:85], v[170:173], v[194:197], v[82:85]
	v_mfma_f32_16x16x32_bf16 v[70:73], v[162:165], v[202:205], v[70:73]
	v_mfma_f32_16x16x32_bf16 v[66:69], v[170:173], v[202:205], v[66:69]
	v_mfma_f32_16x16x32_bf16 v[110:113], v[166:169], v[182:185], v[110:113]
	v_mfma_f32_16x16x32_bf16 v[106:109], v[174:177], v[182:185], v[106:109]
	v_mfma_f32_16x16x32_bf16 v[102:105], v[166:169], v[190:193], v[102:105]
	v_mfma_f32_16x16x32_bf16 v[94:97], v[174:177], v[190:193], v[94:97]
	v_mfma_f32_16x16x32_bf16 v[86:89], v[166:169], v[198:201], v[86:89]
	v_mfma_f32_16x16x32_bf16 v[82:85], v[174:177], v[198:201], v[82:85]
	v_mfma_f32_16x16x32_bf16 v[70:73], v[166:169], v[206:209], v[70:73]
	v_mfma_f32_16x16x32_bf16 v[66:69], v[174:177], v[206:209], v[66:69]
	s_barrier
; #define PG8_STAGE(bufoff, gbase, voff) do { _Pragma("unroll") for (int _i = 0; _i < 2; ++_i) \
;         __builtin_amdgcn_global_load_lds((const unsigned*)((const char*)(gbase) + (voff)[_i]), (PG8_LAS unsigned*)(lds + (bufoff) + ldsw + _i * 8192), 16, 0, 0); } while (0)
; #define PG8_LDA(dst, b, h) do { _Pragma("unroll") for (int m = 0; m < 4; ++m) _Pragma("unroll") for (int k = 0; k < 2; ++k) dst[m][k] = *(const PG8_LAS bf16x8*)(lds + PG8_SA(b, h) + aoff + m * 2048 + k * 1024); } while (0)
; #define PG8_MMA(ai, bj, At, Bt) do { __builtin_amdgcn_s_setprio(1); _Pragma("unroll") for (int m = 0; m < 4; ++m) _Pragma("unroll") for (int n = 0; n < 2; ++n) _Pragma("unroll") for (int k = 0; k < 2; ++k) \
;         acc[ai][bj][m][n] = __builtin_amdgcn_mfma_f32_16x16x32_bf16(Bt[n][k], At[m][k], acc[ai][bj][m][n], 0, 0, 0); __builtin_amdgcn_s_setprio(0); } while (0)
; #define PG8_WAIT_V(n) asm volatile("s_waitcnt vmcnt(" #n ")" ::: "memory")
; #define PG8_WAIT_L(n) asm volatile("s_waitcnt lgkmcnt(" #n ")" ::: "memory")
; #define PG8_BAR __builtin_amdgcn_s_barrier()
; #define PG8_SCHED __builtin_amdgcn_sched_barrier(0)
; template <class Epi, class Sched, bool ALIGN_EPI = false, bool SP2 = false>
; __device__ __forceinline__ void gemm_phase(PG8_LAS unsigned char* lds, const Gemm g, const Sched& S, const Epi& E, const int wv) {
;     ...
;             PG8_LDA(At, 1, 1); PG8_STAGE(PG8_SB(1, 0), b3, voffB); PG8_STAGE(PG8_SB(1, 1), b3 + hstep, voffB); PG8_STAGE(PG8_SA(1, 0), a3, voffA);
;             PG8_WAIT_V(8); PG8_WAIT_L(0); PG8_BAR; PG8_MMA(1, 0, At, B0); PG8_MMA(1, 1, At, B1); PG8_BAR; PG8_SCHED;
	s_setprio 0
	ds_read_b128 v[178:181], v157 offset:49152
	ds_read_b128 v[182:185], v157 offset:50176
	ds_read_b128 v[186:189], v157 offset:51200
	ds_read_b128 v[190:193], v157 offset:52224
	ds_read_b128 v[194:197], v157 offset:53248
	ds_read_b128 v[198:201], v157 offset:54272
	ds_read_b128 v[202:205], v157 offset:55296
	ds_read_b128 v[206:209], v157 offset:56320
	s_add_i32 s22, s45, s24
	v_lshl_add_u64 v[152:153], v[152:153], 0, s[2:3]
	s_mov_b32 m0, s22
	global_load_lds_dwordx4 v[152:153], off
	s_add_i32 m0, s22, 0x2000
	s_add_u32 s20, s20, 0x40080
	v_lshl_add_u64 v[152:153], v[210:211], 0, s[2:3]
	s_addc_u32 s21, s21, 0
	s_add_i32 s22, s46, s24
	global_load_lds_dwordx4 v[152:153], off
	v_lshl_add_u64 v[152:153], s[20:21], 0, v[0:1]
	s_mov_b32 m0, s22
	s_nop 0
	global_load_lds_dwordx4 v[152:153], off
	v_lshl_add_u64 v[152:153], s[20:21], 0, v[130:131]
	s_add_i32 m0, s22, 0x2000
	s_nop 0
	global_load_lds_dwordx4 v[152:153], off
	v_lshl_add_u64 v[152:153], v[212:213], 0, s[2:3]
	s_mov_b32 m0, s33
	s_nop 0
	global_load_lds_dwordx4 v[152:153], off
	v_lshl_add_u64 v[152:153], v[214:215], 0, s[2:3]
	s_mov_b32 m0, s35
	s_nop 0
	global_load_lds_dwordx4 v[152:153], off
	s_waitcnt vmcnt(8)
	s_waitcnt lgkmcnt(0)
	s_setprio 1
	s_barrier
	s_waitcnt lgkmcnt(0)
	v_mfma_f32_16x16x32_bf16 v[62:65], v[140:143], v[178:181], v[62:65]
	v_mfma_f32_16x16x32_bf16 v[58:61], v[148:151], v[178:181], v[58:61]
	v_mfma_f32_16x16x32_bf16 v[46:49], v[140:143], v[186:189], v[46:49]
	v_mfma_f32_16x16x32_bf16 v[42:45], v[148:151], v[186:189], v[42:45]
	v_mfma_f32_16x16x32_bf16 v[30:33], v[140:143], v[194:197], v[30:33]
	v_mfma_f32_16x16x32_bf16 v[26:29], v[148:151], v[194:197], v[26:29]
	v_mfma_f32_16x16x32_bf16 v[14:17], v[140:143], v[202:205], v[14:17]
	v_mfma_f32_16x16x32_bf16 v[10:13], v[148:151], v[202:205], v[10:13]
	v_mfma_f32_16x16x32_bf16 v[62:65], v[144:147], v[182:185], v[62:65]
	v_mfma_f32_16x16x32_bf16 v[58:61], v[158:161], v[182:185], v[58:61]
	v_mfma_f32_16x16x32_bf16 v[46:49], v[144:147], v[190:193], v[46:49]
	v_mfma_f32_16x16x32_bf16 v[42:45], v[158:161], v[190:193], v[42:45]
	v_mfma_f32_16x16x32_bf16 v[30:33], v[144:147], v[198:201], v[30:33]
	v_mfma_f32_16x16x32_bf16 v[26:29], v[158:161], v[198:201], v[26:29]
	v_mfma_f32_16x16x32_bf16 v[14:17], v[144:147], v[206:209], v[14:17]
	v_mfma_f32_16x16x32_bf16 v[10:13], v[158:161], v[206:209], v[10:13]
	s_setprio 0
	s_setprio 1
	v_mfma_f32_16x16x32_bf16 v[54:57], v[162:165], v[178:181], v[54:57]
	v_mfma_f32_16x16x32_bf16 v[50:53], v[170:173], v[178:181], v[50:53]
	v_mfma_f32_16x16x32_bf16 v[38:41], v[162:165], v[186:189], v[38:41]
	v_mfma_f32_16x16x32_bf16 v[34:37], v[170:173], v[186:189], v[34:37]
	v_mfma_f32_16x16x32_bf16 v[22:25], v[162:165], v[194:197], v[22:25]
	v_mfma_f32_16x16x32_bf16 v[18:21], v[170:173], v[194:197], v[18:21]
	v_mfma_f32_16x16x32_bf16 v[6:9], v[162:165], v[202:205], v[6:9]
	v_mfma_f32_16x16x32_bf16 v[2:5], v[170:173], v[202:205], v[2:5]
	v_mfma_f32_16x16x32_bf16 v[54:57], v[166:169], v[182:185], v[54:57]
	v_mfma_f32_16x16x32_bf16 v[50:53], v[174:177], v[182:185], v[50:53]
	v_mfma_f32_16x16x32_bf16 v[38:41], v[166:169], v[190:193], v[38:41]
	v_mfma_f32_16x16x32_bf16 v[34:37], v[174:177], v[190:193], v[34:37]
	v_mfma_f32_16x16x32_bf16 v[22:25], v[166:169], v[198:201], v[22:25]
	v_mfma_f32_16x16x32_bf16 v[18:21], v[174:177], v[198:201], v[18:21]
	v_mfma_f32_16x16x32_bf16 v[6:9], v[166:169], v[206:209], v[6:9]
	v_mfma_f32_16x16x32_bf16 v[2:5], v[174:177], v[206:209], v[2:5]
	s_barrier
	s_setprio 0
	s_add_i32 s44, s44, 2
	s_add_u32 s18, s18, 0x100
	s_addc_u32 s19, s19, 0
	s_add_u32 s42, s42, 0x100
	s_addc_u32 s43, s43, 0
	s_cmp_gt_u32 s44, 13
	s_cbranch_scc0 .LBB0_156
	s_and_b64 vcc, exec, s[6:7]
	s_cbranch_vccz .LBB0_159
	s_barrier

; #define PG8_STAGE(bufoff, gbase, voff) do { _Pragma("unroll") for (int _i = 0; _i < 2; ++_i) \
;         __builtin_amdgcn_global_load_lds((const unsigned*)((const char*)(gbase) + (voff)[_i]), (PG8_LAS unsigned*)(lds + (bufoff) + ldsw + _i * 8192), 16, 0, 0); } while (0)
; #define PG8_LDA(dst, b, h) do { _Pragma("unroll") for (int m = 0; m < 4; ++m) _Pragma("unroll") for (int k = 0; k < 2; ++k) dst[m][k] = *(const PG8_LAS bf16x8*)(lds + PG8_SA(b, h) + aoff + m * 2048 + k * 1024); } while (0)
; #define PG8_LDB(dst, b, h) do { _Pragma("unroll") for (int n = 0; n < 2; ++n) _Pragma("unroll") for (int k = 0; k < 2; ++k) dst[n][k] = *(const PG8_LAS bf16x8*)(lds + PG8_SB(b, h) + boff + n * 2048 + k * 1024); } while (0)
; #define PG8_MMA(ai, bj, At, Bt) do { __builtin_amdgcn_s_setprio(1); _Pragma("unroll") for (int m = 0; m < 4; ++m) _Pragma("unroll") for (int n = 0; n < 2; ++n) _Pragma("unroll") for (int k = 0; k < 2; ++k) \
;         acc[ai][bj][m][n] = __builtin_amdgcn_mfma_f32_16x16x32_bf16(Bt[n][k], At[m][k], acc[ai][bj][m][n], 0, 0, 0); __builtin_amdgcn_s_setprio(0); } while (0)
; #define PG8_WAIT_V(n) asm volatile("s_waitcnt vmcnt(" #n ")" ::: "memory")
; #define PG8_WAIT_L(n) asm volatile("s_waitcnt lgkmcnt(" #n ")" ::: "memory")
; #define PG8_BAR __builtin_amdgcn_s_barrier()
; #define PG8_SCHED __builtin_amdgcn_sched_barrier(0)
; template <class Epi, class Sched, bool ALIGN_EPI = false, bool SP2 = false>
; __device__ __forceinline__ void gemm_phase(PG8_LAS unsigned char* lds, const Gemm g, const Sched& S, const Epi& E, const int wv) {
;     ...
;             const bool last = (t == nt - 2);
;             const char* a1 = cA + (size_t)(t + 1) * kstep;
;             const char* a2 = last ? nA : cA + (size_t)(t + 2) * kstep; const char* b2 = last ? nB : cB + (size_t)(t + 2) * kstep;
;             const char* a3 = a2 + kstep; const char* b3 = b2 + kstep;
;             if (last && has_next) S.a_ready(nxt);
;             if constexpr (SP2) {
;             PG8_LDB(B0, 0, 0); PG8_LDB(B1, 0, 1); PG8_SCHED; PG8_LDA(At, 0, 0); PG8_STAGE(PG8_SA(1, 1), a1 + hstep, voffA);
;             PG8_WAIT_V(8); PG8_WAIT_L(0); PG8_BAR; PG8_MMA(0, 0, At, B0); PG8_MMA(0, 1, At, B1); PG8_BAR; PG8_SCHED;
;             PG8_LDA(At, 0, 1); PG8_STAGE(PG8_SB(0, 0), b2, voffB); PG8_STAGE(PG8_SB(0, 1), b2 + hstep, voffB); PG8_STAGE(PG8_SA(0, 0), a2, voffA);
.LBB0_350:
	s_add_u32 s24, s22, 0xfffc0080
	s_addc_u32 s25, s23, -1
	s_add_i32 s48, 0, 0x10000
	s_cmp_eq_u32 s47, 12
	s_cselect_b32 s27, s13, s25
	s_cselect_b32 s26, s19, s24
	s_cselect_b32 s25, s11, s46
	s_cselect_b32 s24, s33, s45
	s_add_i32 s50, 0, 0x14000
	v_add_u32_e32 v126, s48, v183
	v_add_u32_e32 v168, s50, v183
	ds_read_b128 v[114:117], v126
	ds_read_b128 v[118:121], v126 offset:1024
	ds_read_b128 v[122:125], v126 offset:2048
	ds_read_b128 v[126:129], v126 offset:3072
	ds_read_b128 v[130:133], v168
	ds_read_b128 v[134:137], v168 offset:1024
	ds_read_b128 v[164:167], v168 offset:2048
	ds_read_b128 v[168:171], v168 offset:3072
	v_lshl_add_u64 v[180:181], s[22:23], 0, v[160:161]
	s_add_i32 m0, s21, 0xc000
	ds_read_b128 v[172:175], v185
	ds_read_b128 v[176:179], v185 offset:1024
	ds_read_b128 v[186:189], v185 offset:2048
	ds_read_b128 v[190:193], v185 offset:3072
	ds_read_b128 v[194:197], v185 offset:4096
	ds_read_b128 v[198:201], v185 offset:5120
	ds_read_b128 v[202:205], v185 offset:6144
	ds_read_b128 v[206:209], v185 offset:7168
	global_load_lds_dwordx4 v[180:181], off
	v_lshl_add_u64 v[180:181], s[22:23], 0, v[162:163]
	s_add_i32 m0, s21, 0xe000
	s_nop 0
	global_load_lds_dwordx4 v[180:181], off
	s_waitcnt vmcnt(8)
	s_waitcnt lgkmcnt(0)
	s_setprio 1
	s_barrier
	s_waitcnt lgkmcnt(0)
	v_mfma_f32_16x16x32_bf16 v[150:153], v[114:117], v[172:175], v[150:153]
	v_mfma_f32_16x16x32_bf16 v[146:149], v[122:125], v[172:175], v[146:149]
	v_mfma_f32_16x16x32_bf16 v[110:113], v[114:117], v[186:189], v[110:113]
	v_mfma_f32_16x16x32_bf16 v[106:109], v[122:125], v[186:189], v[106:109]
	v_mfma_f32_16x16x32_bf16 v[94:97], v[114:117], v[194:197], v[94:97]
	v_mfma_f32_16x16x32_bf16 v[90:93], v[122:125], v[194:197], v[90:93]
	v_mfma_f32_16x16x32_bf16 v[78:81], v[114:117], v[202:205], v[78:81]
	v_mfma_f32_16x16x32_bf16 v[74:77], v[122:125], v[202:205], v[74:77]
	v_mfma_f32_16x16x32_bf16 v[150:153], v[118:121], v[176:179], v[150:153]
	v_mfma_f32_16x16x32_bf16 v[146:149], v[126:129], v[176:179], v[146:149]
	v_mfma_f32_16x16x32_bf16 v[110:113], v[118:121], v[190:193], v[110:113]
	v_mfma_f32_16x16x32_bf16 v[106:109], v[126:129], v[190:193], v[106:109]
	v_mfma_f32_16x16x32_bf16 v[94:97], v[118:121], v[198:201], v[94:97]
	v_mfma_f32_16x16x32_bf16 v[90:93], v[126:129], v[198:201], v[90:93]
	v_mfma_f32_16x16x32_bf16 v[78:81], v[118:121], v[206:209], v[78:81]
	v_mfma_f32_16x16x32_bf16 v[74:77], v[126:129], v[206:209], v[74:77]
	s_setprio 0
	s_setprio 1
	v_mfma_f32_16x16x32_bf16 v[142:145], v[130:133], v[172:175], v[142:145]
	v_mfma_f32_16x16x32_bf16 v[138:141], v[164:167], v[172:175], v[138:141]
	v_mfma_f32_16x16x32_bf16 v[102:105], v[130:133], v[186:189], v[102:105]
	v_mfma_f32_16x16x32_bf16 v[98:101], v[164:167], v[186:189], v[98:101]
	v_mfma_f32_16x16x32_bf16 v[86:89], v[130:133], v[194:197], v[86:89]
	v_mfma_f32_16x16x32_bf16 v[82:85], v[164:167], v[194:197], v[82:85]
	v_mfma_f32_16x16x32_bf16 v[70:73], v[130:133], v[202:205], v[70:73]
	v_mfma_f32_16x16x32_bf16 v[66:69], v[164:167], v[202:205], v[66:69]
	v_mfma_f32_16x16x32_bf16 v[142:145], v[134:137], v[176:179], v[142:145]
	v_mfma_f32_16x16x32_bf16 v[138:141], v[168:171], v[176:179], v[138:141]
	v_mfma_f32_16x16x32_bf16 v[102:105], v[134:137], v[190:193], v[102:105]
	v_mfma_f32_16x16x32_bf16 v[98:101], v[168:171], v[190:193], v[98:101]
	v_mfma_f32_16x16x32_bf16 v[86:89], v[134:137], v[198:201], v[86:89]
	v_mfma_f32_16x16x32_bf16 v[82:85], v[168:171], v[198:201], v[82:85]
	v_mfma_f32_16x16x32_bf16 v[70:73], v[134:137], v[206:209], v[70:73]
	v_mfma_f32_16x16x32_bf16 v[66:69], v[168:171], v[206:209], v[66:69]
	s_barrier
	s_setprio 0
	ds_read_b128 v[172:175], v185 offset:16384
	ds_read_b128 v[176:179], v185 offset:17408
	ds_read_b128 v[186:189], v185 offset:18432
	ds_read_b128 v[190:193], v185 offset:19456
	ds_read_b128 v[194:197], v185 offset:20480
	ds_read_b128 v[198:201], v185 offset:21504
	ds_read_b128 v[202:205], v185 offset:22528
	ds_read_b128 v[206:209], v185 offset:23552
	s_add_i32 s48, s48, s36
	v_lshl_add_u64 v[180:181], s[24:25], 0, v[0:1]
	s_mov_b32 m0, s48
	global_load_lds_dwordx4 v[180:181], off
	s_add_i32 m0, s48, 0x2000
	s_add_u32 s48, s24, 0x40000
	v_lshl_add_u64 v[210:211], s[24:25], 0, v[158:159]
	s_addc_u32 s49, s25, 0
	s_add_i32 s50, s50, s36
	global_load_lds_dwordx4 v[210:211], off
	v_lshl_add_u64 v[212:213], s[48:49], 0, v[0:1]
	s_mov_b32 m0, s50
	v_lshl_add_u64 v[214:215], s[26:27], 0, v[156:157]
	global_load_lds_dwordx4 v[212:213], off
	v_lshl_add_u64 v[212:213], s[48:49], 0, v[158:159]
	s_add_i32 m0, s50, 0x2000
	s_nop 0
	global_load_lds_dwordx4 v[212:213], off
	v_lshl_add_u64 v[212:213], s[26:27], 0, v[154:155]
	s_mov_b32 m0, s21
	s_nop 0
	global_load_lds_dwordx4 v[212:213], off
	s_mov_b32 m0, s37
	s_nop 0
	global_load_lds_dwordx4 v[214:215], off
	s_waitcnt vmcnt(8)
	s_waitcnt lgkmcnt(0)
	s_setprio 1
	s_barrier
; #define PG8_STAGE(bufoff, gbase, voff) do { _Pragma("unroll") for (int _i = 0; _i < 2; ++_i) \
;         __builtin_amdgcn_global_load_lds((const unsigned*)((const char*)(gbase) + (voff)[_i]), (PG8_LAS unsigned*)(lds + (bufoff) + ldsw + _i * 8192), 16, 0, 0); } while (0)
; #define PG8_LDA(dst, b, h) do { _Pragma("unroll") for (int m = 0; m < 4; ++m) _Pragma("unroll") for (int k = 0; k < 2; ++k) dst[m][k] = *(const PG8_LAS bf16x8*)(lds + PG8_SA(b, h) + aoff + m * 2048 + k * 1024); } while (0)
; #define PG8_LDB(dst, b, h) do { _Pragma("unroll") for (int n = 0; n < 2; ++n) _Pragma("unroll") for (int k = 0; k < 2; ++k) dst[n][k] = *(const PG8_LAS bf16x8*)(lds + PG8_SB(b, h) + boff + n * 2048 + k * 1024); } while (0)
; #define PG8_MMA(ai, bj, At, Bt) do { __builtin_amdgcn_s_setprio(1); _Pragma("unroll") for (int m = 0; m < 4; ++m) _Pragma("unroll") for (int n = 0; n < 2; ++n) _Pragma("unroll") for (int k = 0; k < 2; ++k) \
;         acc[ai][bj][m][n] = __builtin_amdgcn_mfma_f32_16x16x32_bf16(Bt[n][k], At[m][k], acc[ai][bj][m][n], 0, 0, 0); __builtin_amdgcn_s_setprio(0); } while (0)
; #define PG8_WAIT_V(n) asm volatile("s_waitcnt vmcnt(" #n ")" ::: "memory")
; #define PG8_WAIT_L(n) asm volatile("s_waitcnt lgkmcnt(" #n ")" ::: "memory")
; #define PG8_BAR __builtin_amdgcn_s_barrier()
; #define PG8_SCHED __builtin_amdgcn_sched_barrier(0)
; template <class Epi, class Sched, bool ALIGN_EPI = false, bool SP2 = false>
; __device__ __forceinline__ void gemm_phase(PG8_LAS unsigned char* lds, const Gemm g, const Sched& S, const Epi& E, const int wv) {
;     ...
;             PG8_WAIT_V(8); PG8_WAIT_L(0); PG8_BAR; PG8_MMA(1, 0, At, B0); PG8_MMA(1, 1, At, B1); PG8_BAR; PG8_SCHED;
;             PG8_LDB(B0, 1, 0); PG8_LDB(B1, 1, 1); PG8_SCHED; PG8_LDA(At, 1, 0); PG8_STAGE(PG8_SA(0, 1), a2 + hstep, voffA);
;             PG8_WAIT_V(8); PG8_WAIT_L(0); PG8_BAR; PG8_MMA(0, 0, At, B0); PG8_MMA(0, 1, At, B1); PG8_BAR; PG8_SCHED;
	s_waitcnt lgkmcnt(0)
	v_mfma_f32_16x16x32_bf16 v[62:65], v[114:117], v[172:175], v[62:65]
	v_mfma_f32_16x16x32_bf16 v[58:61], v[122:125], v[172:175], v[58:61]
	v_mfma_f32_16x16x32_bf16 v[46:49], v[114:117], v[186:189], v[46:49]
	v_mfma_f32_16x16x32_bf16 v[42:45], v[122:125], v[186:189], v[42:45]
	v_mfma_f32_16x16x32_bf16 v[30:33], v[114:117], v[194:197], v[30:33]
	v_mfma_f32_16x16x32_bf16 v[26:29], v[122:125], v[194:197], v[26:29]
	v_mfma_f32_16x16x32_bf16 v[14:17], v[114:117], v[202:205], v[14:17]
	v_mfma_f32_16x16x32_bf16 v[10:13], v[122:125], v[202:205], v[10:13]
	v_mfma_f32_16x16x32_bf16 v[62:65], v[118:121], v[176:179], v[62:65]
	v_mfma_f32_16x16x32_bf16 v[58:61], v[126:129], v[176:179], v[58:61]
	v_mfma_f32_16x16x32_bf16 v[46:49], v[118:121], v[190:193], v[46:49]
	v_mfma_f32_16x16x32_bf16 v[42:45], v[126:129], v[190:193], v[42:45]
	v_mfma_f32_16x16x32_bf16 v[30:33], v[118:121], v[198:201], v[30:33]
	v_mfma_f32_16x16x32_bf16 v[26:29], v[126:129], v[198:201], v[26:29]
	v_mfma_f32_16x16x32_bf16 v[14:17], v[118:121], v[206:209], v[14:17]
	v_mfma_f32_16x16x32_bf16 v[10:13], v[126:129], v[206:209], v[10:13]
	s_setprio 0
	s_setprio 1
	v_mfma_f32_16x16x32_bf16 v[54:57], v[130:133], v[172:175], v[54:57]
	v_mfma_f32_16x16x32_bf16 v[50:53], v[164:167], v[172:175], v[50:53]
	v_mfma_f32_16x16x32_bf16 v[38:41], v[130:133], v[186:189], v[38:41]
	v_mfma_f32_16x16x32_bf16 v[34:37], v[164:167], v[186:189], v[34:37]
	v_mfma_f32_16x16x32_bf16 v[22:25], v[130:133], v[194:197], v[22:25]
	v_mfma_f32_16x16x32_bf16 v[18:21], v[164:167], v[194:197], v[18:21]
	v_mfma_f32_16x16x32_bf16 v[6:9], v[130:133], v[202:205], v[6:9]
	v_mfma_f32_16x16x32_bf16 v[2:5], v[164:167], v[202:205], v[2:5]
	v_mfma_f32_16x16x32_bf16 v[54:57], v[134:137], v[176:179], v[54:57]
	v_mfma_f32_16x16x32_bf16 v[50:53], v[168:171], v[176:179], v[50:53]
	v_mfma_f32_16x16x32_bf16 v[38:41], v[134:137], v[190:193], v[38:41]
	v_mfma_f32_16x16x32_bf16 v[34:37], v[168:171], v[190:193], v[34:37]
	v_mfma_f32_16x16x32_bf16 v[22:25], v[134:137], v[198:201], v[22:25]
	v_mfma_f32_16x16x32_bf16 v[18:21], v[168:171], v[198:201], v[18:21]
	v_mfma_f32_16x16x32_bf16 v[6:9], v[134:137], v[206:209], v[6:9]
	v_mfma_f32_16x16x32_bf16 v[2:5], v[168:171], v[206:209], v[2:5]
	s_barrier
	s_setprio 0
	s_add_i32 s48, 0, 0x18000
	s_add_i32 s49, 0, 0x1c000
	v_add_u32_e32 v126, s48, v183
	v_add_u32_e32 v168, s49, v183
	ds_read_b128 v[114:117], v126
	ds_read_b128 v[118:121], v126 offset:1024
	ds_read_b128 v[122:125], v126 offset:2048
	ds_read_b128 v[126:129], v126 offset:3072
	ds_read_b128 v[130:133], v168
	ds_read_b128 v[134:137], v168 offset:1024
	ds_read_b128 v[164:167], v168 offset:2048
	ds_read_b128 v[168:171], v168 offset:3072
	s_add_u32 s26, s26, 0x40000
	s_addc_u32 s27, s27, 0
	s_mov_b32 m0, s38
	v_lshl_add_u64 v[216:217], s[26:27], 0, v[154:155]
	ds_read_b128 v[172:175], v185 offset:32768
	ds_read_b128 v[176:179], v185 offset:33792
	ds_read_b128 v[186:189], v185 offset:34816
	ds_read_b128 v[190:193], v185 offset:35840
	ds_read_b128 v[194:197], v185 offset:36864
	ds_read_b128 v[198:201], v185 offset:37888
	ds_read_b128 v[202:205], v185 offset:38912
	ds_read_b128 v[206:209], v185 offset:39936
	global_load_lds_dwordx4 v[216:217], off
	v_lshl_add_u64 v[216:217], s[26:27], 0, v[156:157]
	s_mov_b32 m0, s39
	s_nop 0
	global_load_lds_dwordx4 v[216:217], off
	s_waitcnt vmcnt(8)
	s_waitcnt lgkmcnt(0)
	s_setprio 1
	s_barrier
	s_waitcnt lgkmcnt(0)
	v_mfma_f32_16x16x32_bf16 v[150:153], v[114:117], v[172:175], v[150:153]
	v_mfma_f32_16x16x32_bf16 v[146:149], v[122:125], v[172:175], v[146:149]
	v_mfma_f32_16x16x32_bf16 v[110:113], v[114:117], v[186:189], v[110:113]
	v_mfma_f32_16x16x32_bf16 v[106:109], v[122:125], v[186:189], v[106:109]
	v_mfma_f32_16x16x32_bf16 v[94:97], v[114:117], v[194:197], v[94:97]
	v_mfma_f32_16x16x32_bf16 v[90:93], v[122:125], v[194:197], v[90:93]
	v_mfma_f32_16x16x32_bf16 v[78:81], v[114:117], v[202:205], v[78:81]
	v_mfma_f32_16x16x32_bf16 v[74:77], v[122:125], v[202:205], v[74:77]
	v_mfma_f32_16x16x32_bf16 v[150:153], v[118:121], v[176:179], v[150:153]
	v_mfma_f32_16x16x32_bf16 v[146:149], v[126:129], v[176:179], v[146:149]
	v_mfma_f32_16x16x32_bf16 v[110:113], v[118:121], v[190:193], v[110:113]
	v_mfma_f32_16x16x32_bf16 v[106:109], v[126:129], v[190:193], v[106:109]
	v_mfma_f32_16x16x32_bf16 v[94:97], v[118:121], v[198:201], v[94:97]
	v_mfma_f32_16x16x32_bf16 v[90:93], v[126:129], v[198:201], v[90:93]
	v_mfma_f32_16x16x32_bf16 v[78:81], v[118:121], v[206:209], v[78:81]
	v_mfma_f32_16x16x32_bf16 v[74:77], v[126:129], v[206:209], v[74:77]
	s_setprio 0
	s_setprio 1
	v_mfma_f32_16x16x32_bf16 v[142:145], v[130:133], v[172:175], v[142:145]
	v_mfma_f32_16x16x32_bf16 v[138:141], v[164:167], v[172:175], v[138:141]
	v_mfma_f32_16x16x32_bf16 v[102:105], v[130:133], v[186:189], v[102:105]
	v_mfma_f32_16x16x32_bf16 v[98:101], v[164:167], v[186:189], v[98:101]
	v_mfma_f32_16x16x32_bf16 v[86:89], v[130:133], v[194:197], v[86:89]
	v_mfma_f32_16x16x32_bf16 v[82:85], v[164:167], v[194:197], v[82:85]
	v_mfma_f32_16x16x32_bf16 v[70:73], v[130:133], v[202:205], v[70:73]
	v_mfma_f32_16x16x32_bf16 v[66:69], v[164:167], v[202:205], v[66:69]
	v_mfma_f32_16x16x32_bf16 v[142:145], v[134:137], v[176:179], v[142:145]
	v_mfma_f32_16x16x32_bf16 v[138:141], v[168:171], v[176:179], v[138:141]
	v_mfma_f32_16x16x32_bf16 v[102:105], v[134:137], v[190:193], v[102:105]
	v_mfma_f32_16x16x32_bf16 v[98:101], v[168:171], v[190:193], v[98:101]
	v_mfma_f32_16x16x32_bf16 v[86:89], v[134:137], v[198:201], v[86:89]
	v_mfma_f32_16x16x32_bf16 v[82:85], v[168:171], v[198:201], v[82:85]
	v_mfma_f32_16x16x32_bf16 v[70:73], v[134:137], v[206:209], v[70:73]
	v_mfma_f32_16x16x32_bf16 v[66:69], v[168:171], v[206:209], v[66:69]
	s_barrier
; #define PG8_STAGE(bufoff, gbase, voff) do { _Pragma("unroll") for (int _i = 0; _i < 2; ++_i) \
;         __builtin_amdgcn_global_load_lds((const unsigned*)((const char*)(gbase) + (voff)[_i]), (PG8_LAS unsigned*)(lds + (bufoff) + ldsw + _i * 8192), 16, 0, 0); } while (0)
; #define PG8_LDA(dst, b, h) do { _Pragma("unroll") for (int m = 0; m < 4; ++m) _Pragma("unroll") for (int k = 0; k < 2; ++k) dst[m][k] = *(const PG8_LAS bf16x8*)(lds + PG8_SA(b, h) + aoff + m * 2048 + k * 1024); } while (0)
; #define PG8_MMA(ai, bj, At, Bt) do { __builtin_amdgcn_s_setprio(1); _Pragma("unroll") for (int m = 0; m < 4; ++m) _Pragma("unroll") for (int n = 0; n < 2; ++n) _Pragma("unroll") for (int k = 0; k < 2; ++k) \
;         acc[ai][bj][m][n] = __builtin_amdgcn_mfma_f32_16x16x32_bf16(Bt[n][k], At[m][k], acc[ai][bj][m][n], 0, 0, 0); __builtin_amdgcn_s_setprio(0); } while (0)
; #define PG8_WAIT_V(n) asm volatile("s_waitcnt vmcnt(" #n ")" ::: "memory")
; #define PG8_WAIT_L(n) asm volatile("s_waitcnt lgkmcnt(" #n ")" ::: "memory")
; #define PG8_BAR __builtin_amdgcn_s_barrier()
; #define PG8_SCHED __builtin_amdgcn_sched_barrier(0)
; template <class Epi, class Sched, bool ALIGN_EPI = false, bool SP2 = false>
; __device__ __forceinline__ void gemm_phase(PG8_LAS unsigned char* lds, const Gemm g, const Sched& S, const Epi& E, const int wv) {
;     ...
;             PG8_LDA(At, 1, 1); PG8_STAGE(PG8_SB(1, 0), b3, voffB); PG8_STAGE(PG8_SB(1, 1), b3 + hstep, voffB); PG8_STAGE(PG8_SA(1, 0), a3, voffA);
;             PG8_WAIT_V(8); PG8_WAIT_L(0); PG8_BAR; PG8_MMA(1, 0, At, B0); PG8_MMA(1, 1, At, B1); PG8_BAR; PG8_SCHED;
	s_setprio 0
	ds_read_b128 v[172:175], v185 offset:49152
	ds_read_b128 v[176:179], v185 offset:50176
	ds_read_b128 v[186:189], v185 offset:51200
	ds_read_b128 v[190:193], v185 offset:52224
	ds_read_b128 v[194:197], v185 offset:53248
	ds_read_b128 v[198:201], v185 offset:54272
	ds_read_b128 v[202:205], v185 offset:55296
	ds_read_b128 v[206:209], v185 offset:56320
	s_add_i32 s26, s48, s36
	v_lshl_add_u64 v[180:181], v[180:181], 0, s[2:3]
	s_mov_b32 m0, s26
	global_load_lds_dwordx4 v[180:181], off
	s_add_i32 m0, s26, 0x2000
	s_add_u32 s24, s24, 0x40080
	v_lshl_add_u64 v[180:181], v[210:211], 0, s[2:3]
	s_addc_u32 s25, s25, 0
	s_add_i32 s26, s49, s36
	global_load_lds_dwordx4 v[180:181], off
	v_lshl_add_u64 v[180:181], s[24:25], 0, v[0:1]
	s_mov_b32 m0, s26
	s_nop 0
	global_load_lds_dwordx4 v[180:181], off
	v_lshl_add_u64 v[180:181], s[24:25], 0, v[158:159]
	s_add_i32 m0, s26, 0x2000
	s_nop 0
	global_load_lds_dwordx4 v[180:181], off
	v_lshl_add_u64 v[180:181], v[212:213], 0, s[2:3]
	s_mov_b32 m0, s40
	s_nop 0
	global_load_lds_dwordx4 v[180:181], off
	v_lshl_add_u64 v[180:181], v[214:215], 0, s[2:3]
	s_mov_b32 m0, s41
	s_nop 0
	global_load_lds_dwordx4 v[180:181], off
	s_waitcnt vmcnt(8)
	s_waitcnt lgkmcnt(0)
	s_setprio 1
	s_barrier
	s_waitcnt lgkmcnt(0)
	v_mfma_f32_16x16x32_bf16 v[62:65], v[114:117], v[172:175], v[62:65]
	v_mfma_f32_16x16x32_bf16 v[58:61], v[122:125], v[172:175], v[58:61]
	v_mfma_f32_16x16x32_bf16 v[46:49], v[114:117], v[186:189], v[46:49]
	v_mfma_f32_16x16x32_bf16 v[42:45], v[122:125], v[186:189], v[42:45]
	v_mfma_f32_16x16x32_bf16 v[30:33], v[114:117], v[194:197], v[30:33]
	v_mfma_f32_16x16x32_bf16 v[26:29], v[122:125], v[194:197], v[26:29]
	v_mfma_f32_16x16x32_bf16 v[14:17], v[114:117], v[202:205], v[14:17]
	v_mfma_f32_16x16x32_bf16 v[10:13], v[122:125], v[202:205], v[10:13]
	v_mfma_f32_16x16x32_bf16 v[62:65], v[118:121], v[176:179], v[62:65]
	v_mfma_f32_16x16x32_bf16 v[58:61], v[126:129], v[176:179], v[58:61]
	v_mfma_f32_16x16x32_bf16 v[46:49], v[118:121], v[190:193], v[46:49]
	v_mfma_f32_16x16x32_bf16 v[42:45], v[126:129], v[190:193], v[42:45]
	v_mfma_f32_16x16x32_bf16 v[30:33], v[118:121], v[198:201], v[30:33]
	v_mfma_f32_16x16x32_bf16 v[26:29], v[126:129], v[198:201], v[26:29]
	v_mfma_f32_16x16x32_bf16 v[14:17], v[118:121], v[206:209], v[14:17]
	v_mfma_f32_16x16x32_bf16 v[10:13], v[126:129], v[206:209], v[10:13]
	s_setprio 0
	s_setprio 1
	v_mfma_f32_16x16x32_bf16 v[54:57], v[130:133], v[172:175], v[54:57]
	v_mfma_f32_16x16x32_bf16 v[50:53], v[164:167], v[172:175], v[50:53]
	v_mfma_f32_16x16x32_bf16 v[38:41], v[130:133], v[186:189], v[38:41]
	v_mfma_f32_16x16x32_bf16 v[34:37], v[164:167], v[186:189], v[34:37]
	v_mfma_f32_16x16x32_bf16 v[22:25], v[130:133], v[194:197], v[22:25]
	v_mfma_f32_16x16x32_bf16 v[18:21], v[164:167], v[194:197], v[18:21]
	v_mfma_f32_16x16x32_bf16 v[6:9], v[130:133], v[202:205], v[6:9]
	v_mfma_f32_16x16x32_bf16 v[2:5], v[164:167], v[202:205], v[2:5]
	v_mfma_f32_16x16x32_bf16 v[54:57], v[134:137], v[176:179], v[54:57]
	v_mfma_f32_16x16x32_bf16 v[50:53], v[168:171], v[176:179], v[50:53]
	v_mfma_f32_16x16x32_bf16 v[38:41], v[134:137], v[190:193], v[38:41]
	v_mfma_f32_16x16x32_bf16 v[34:37], v[168:171], v[190:193], v[34:37]
	v_mfma_f32_16x16x32_bf16 v[22:25], v[134:137], v[198:201], v[22:25]
	v_mfma_f32_16x16x32_bf16 v[18:21], v[168:171], v[198:201], v[18:21]
	v_mfma_f32_16x16x32_bf16 v[6:9], v[134:137], v[206:209], v[6:9]
	v_mfma_f32_16x16x32_bf16 v[2:5], v[168:171], v[206:209], v[2:5]
	s_barrier
	s_setprio 0
	s_add_i32 s47, s47, 2
	s_add_u32 s22, s22, 0x100
	s_addc_u32 s23, s23, 0
	s_add_u32 s45, s45, 0x100
	s_addc_u32 s46, s46, 0
	s_cmp_gt_u32 s47, 13
	s_cbranch_scc0 .LBB0_350
	s_and_b64 vcc, exec, s[8:9]
	s_cbranch_vccz .LBB0_353
	s_barrier

; #define PG8_STAGE(bufoff, gbase, voff) do { _Pragma("unroll") for (int _i = 0; _i < 2; ++_i) \
;         __builtin_amdgcn_global_load_lds((const unsigned*)((const char*)(gbase) + (voff)[_i]), (PG8_LAS unsigned*)(lds + (bufoff) + ldsw + _i * 8192), 16, 0, 0); } while (0)
; #define PG8_LDA(dst, b, h) do { _Pragma("unroll") for (int m = 0; m < 4; ++m) _Pragma("unroll") for (int k = 0; k < 2; ++k) dst[m][k] = *(const PG8_LAS bf16x8*)(lds + PG8_SA(b, h) + aoff + m * 2048 + k * 1024); } while (0)
; #define PG8_LDB(dst, b, h) do { _Pragma("unroll") for (int n = 0; n < 2; ++n) _Pragma("unroll") for (int k = 0; k < 2; ++k) dst[n][k] = *(const PG8_LAS bf16x8*)(lds + PG8_SB(b, h) + boff + n * 2048 + k * 1024); } while (0)
; #define PG8_MMA(ai, bj, At, Bt) do { __builtin_amdgcn_s_setprio(1); _Pragma("unroll") for (int m = 0; m < 4; ++m) _Pragma("unroll") for (int n = 0; n < 2; ++n) _Pragma("unroll") for (int k = 0; k < 2; ++k) \
;         acc[ai][bj][m][n] = __builtin_amdgcn_mfma_f32_16x16x32_bf16(Bt[n][k], At[m][k], acc[ai][bj][m][n], 0, 0, 0); __builtin_amdgcn_s_setprio(0); } while (0)
; #define PG8_WAIT_V(n) asm volatile("s_waitcnt vmcnt(" #n ")" ::: "memory")
; #define PG8_WAIT_L(n) asm volatile("s_waitcnt lgkmcnt(" #n ")" ::: "memory")
; #define PG8_BAR __builtin_amdgcn_s_barrier()
; #define PG8_SCHED __builtin_amdgcn_sched_barrier(0)
; template <class Epi, class Sched, bool ALIGN_EPI = false, bool SP2 = false>
; __device__ __forceinline__ void gemm_phase(PG8_LAS unsigned char* lds, const Gemm g, const Sched& S, const Epi& E, const int wv) {
;     ...
;             const bool last = (t == nt - 2);
;             const char* a1 = cA + (size_t)(t + 1) * kstep;
;             const char* a2 = last ? nA : cA + (size_t)(t + 2) * kstep; const char* b2 = last ? nB : cB + (size_t)(t + 2) * kstep;
;             const char* a3 = a2 + kstep; const char* b3 = b2 + kstep;
;             if (last && has_next) S.a_ready(nxt);
;             if constexpr (SP2) {
;             PG8_LDB(B0, 0, 0); PG8_LDB(B1, 0, 1); PG8_SCHED; PG8_LDA(At, 0, 0); PG8_STAGE(PG8_SA(1, 1), a1 + hstep, voffA);
;             PG8_WAIT_V(8); PG8_WAIT_L(0); PG8_BAR; PG8_MMA(0, 0, At, B0); PG8_MMA(0, 1, At, B1); PG8_BAR; PG8_SCHED;
;             PG8_LDA(At, 0, 1); PG8_STAGE(PG8_SB(0, 0), b2, voffB); PG8_STAGE(PG8_SB(0, 1), b2 + hstep, voffB); PG8_STAGE(PG8_SA(0, 0), a2, voffA);
.LBB0_428:
	s_add_u32 s20, s18, 0xfffc0080
	s_addc_u32 s21, s19, -1
	s_add_i32 s46, 0, 0x10000
	s_cmp_eq_u32 s45, 12
	s_cselect_b32 s23, s11, s21
	s_cselect_b32 s22, s33, s20
	s_cselect_b32 s21, s9, s44
	s_cselect_b32 s20, s42, s43
	s_add_i32 s48, 0, 0x14000
	v_add_u32_e32 v152, s46, v166
	v_add_u32_e32 v164, s48, v166
	ds_read_b128 v[140:143], v152
	ds_read_b128 v[144:147], v152 offset:1024
	ds_read_b128 v[148:151], v152 offset:2048
	ds_read_b128 v[152:155], v152 offset:3072
	ds_read_b128 v[156:159], v164
	ds_read_b128 v[160:163], v164 offset:1024
	ds_read_b128 v[170:173], v164 offset:2048
	ds_read_b128 v[174:177], v164 offset:3072
	v_lshl_add_u64 v[210:211], s[18:19], 0, v[136:137]
	s_add_i32 m0, s30, 0xc000
	ds_read_b128 v[178:181], v168
	ds_read_b128 v[182:185], v168 offset:1024
	ds_read_b128 v[186:189], v168 offset:2048
	ds_read_b128 v[190:193], v168 offset:3072
	ds_read_b128 v[194:197], v168 offset:4096
	ds_read_b128 v[198:201], v168 offset:5120
	ds_read_b128 v[202:205], v168 offset:6144
	ds_read_b128 v[206:209], v168 offset:7168
	global_load_lds_dwordx4 v[210:211], off
	v_lshl_add_u64 v[210:211], s[18:19], 0, v[138:139]
	s_add_i32 m0, s30, 0xe000
	s_nop 0
	global_load_lds_dwordx4 v[210:211], off
	s_waitcnt vmcnt(8)
	s_waitcnt lgkmcnt(0)
	s_setprio 1
	s_barrier
	s_waitcnt lgkmcnt(0)
	v_mfma_f32_16x16x32_bf16 v[126:129], v[140:143], v[178:181], v[126:129]
	v_mfma_f32_16x16x32_bf16 v[118:121], v[148:151], v[178:181], v[118:121]
	v_mfma_f32_16x16x32_bf16 v[110:113], v[140:143], v[186:189], v[110:113]
	v_mfma_f32_16x16x32_bf16 v[102:105], v[148:151], v[186:189], v[102:105]
	v_mfma_f32_16x16x32_bf16 v[94:97], v[140:143], v[194:197], v[94:97]
	v_mfma_f32_16x16x32_bf16 v[86:89], v[148:151], v[194:197], v[86:89]
	v_mfma_f32_16x16x32_bf16 v[78:81], v[140:143], v[202:205], v[78:81]
	v_mfma_f32_16x16x32_bf16 v[70:73], v[148:151], v[202:205], v[70:73]
	v_mfma_f32_16x16x32_bf16 v[126:129], v[144:147], v[182:185], v[126:129]
	v_mfma_f32_16x16x32_bf16 v[118:121], v[152:155], v[182:185], v[118:121]
	v_mfma_f32_16x16x32_bf16 v[110:113], v[144:147], v[190:193], v[110:113]
	v_mfma_f32_16x16x32_bf16 v[102:105], v[152:155], v[190:193], v[102:105]
	v_mfma_f32_16x16x32_bf16 v[94:97], v[144:147], v[198:201], v[94:97]
	v_mfma_f32_16x16x32_bf16 v[86:89], v[152:155], v[198:201], v[86:89]
	v_mfma_f32_16x16x32_bf16 v[78:81], v[144:147], v[206:209], v[78:81]
	v_mfma_f32_16x16x32_bf16 v[70:73], v[152:155], v[206:209], v[70:73]
	s_setprio 0
	s_setprio 1
	v_mfma_f32_16x16x32_bf16 v[122:125], v[156:159], v[178:181], v[122:125]
	v_mfma_f32_16x16x32_bf16 v[114:117], v[170:173], v[178:181], v[114:117]
	v_mfma_f32_16x16x32_bf16 v[106:109], v[156:159], v[186:189], v[106:109]
	v_mfma_f32_16x16x32_bf16 v[98:101], v[170:173], v[186:189], v[98:101]
	v_mfma_f32_16x16x32_bf16 v[90:93], v[156:159], v[194:197], v[90:93]
	v_mfma_f32_16x16x32_bf16 v[82:85], v[170:173], v[194:197], v[82:85]
	v_mfma_f32_16x16x32_bf16 v[74:77], v[156:159], v[202:205], v[74:77]
	v_mfma_f32_16x16x32_bf16 v[66:69], v[170:173], v[202:205], v[66:69]
	v_mfma_f32_16x16x32_bf16 v[122:125], v[160:163], v[182:185], v[122:125]
	v_mfma_f32_16x16x32_bf16 v[114:117], v[174:177], v[182:185], v[114:117]
	v_mfma_f32_16x16x32_bf16 v[106:109], v[160:163], v[190:193], v[106:109]
	v_mfma_f32_16x16x32_bf16 v[98:101], v[174:177], v[190:193], v[98:101]
	v_mfma_f32_16x16x32_bf16 v[90:93], v[160:163], v[198:201], v[90:93]
	v_mfma_f32_16x16x32_bf16 v[82:85], v[174:177], v[198:201], v[82:85]
	v_mfma_f32_16x16x32_bf16 v[74:77], v[160:163], v[206:209], v[74:77]
	v_mfma_f32_16x16x32_bf16 v[66:69], v[174:177], v[206:209], v[66:69]
	s_barrier
	s_setprio 0
	ds_read_b128 v[178:181], v168 offset:16384
	ds_read_b128 v[182:185], v168 offset:17408
	ds_read_b128 v[186:189], v168 offset:18432
	ds_read_b128 v[190:193], v168 offset:19456
	ds_read_b128 v[194:197], v168 offset:20480
	ds_read_b128 v[198:201], v168 offset:21504
	ds_read_b128 v[202:205], v168 offset:22528
	ds_read_b128 v[206:209], v168 offset:23552
	s_add_i32 s46, s46, s29
	v_lshl_add_u64 v[210:211], s[20:21], 0, v[0:1]
	s_mov_b32 m0, s46
	global_load_lds_dwordx4 v[210:211], off
	s_add_i32 m0, s46, 0x2000
	s_add_u32 s46, s20, 0x40000
	v_lshl_add_u64 v[212:213], s[20:21], 0, v[130:131]
	s_addc_u32 s47, s21, 0
	s_add_i32 s48, s48, s29
	global_load_lds_dwordx4 v[212:213], off
	v_lshl_add_u64 v[214:215], s[46:47], 0, v[0:1]
	s_mov_b32 m0, s48
	v_lshl_add_u64 v[216:217], s[22:23], 0, v[132:133]
	global_load_lds_dwordx4 v[214:215], off
	v_lshl_add_u64 v[214:215], s[46:47], 0, v[130:131]
	s_add_i32 m0, s48, 0x2000
	s_nop 0
	global_load_lds_dwordx4 v[214:215], off
	v_lshl_add_u64 v[214:215], s[22:23], 0, v[134:135]
	s_mov_b32 m0, s30
	s_nop 0
	global_load_lds_dwordx4 v[214:215], off
	s_mov_b32 m0, s31
	s_nop 0
	global_load_lds_dwordx4 v[216:217], off
	s_waitcnt vmcnt(8)
	s_waitcnt lgkmcnt(0)
	s_setprio 1
	s_barrier
; #define PG8_STAGE(bufoff, gbase, voff) do { _Pragma("unroll") for (int _i = 0; _i < 2; ++_i) \
;         __builtin_amdgcn_global_load_lds((const unsigned*)((const char*)(gbase) + (voff)[_i]), (PG8_LAS unsigned*)(lds + (bufoff) + ldsw + _i * 8192), 16, 0, 0); } while (0)
; #define PG8_LDA(dst, b, h) do { _Pragma("unroll") for (int m = 0; m < 4; ++m) _Pragma("unroll") for (int k = 0; k < 2; ++k) dst[m][k] = *(const PG8_LAS bf16x8*)(lds + PG8_SA(b, h) + aoff + m * 2048 + k * 1024); } while (0)
; #define PG8_LDB(dst, b, h) do { _Pragma("unroll") for (int n = 0; n < 2; ++n) _Pragma("unroll") for (int k = 0; k < 2; ++k) dst[n][k] = *(const PG8_LAS bf16x8*)(lds + PG8_SB(b, h) + boff + n * 2048 + k * 1024); } while (0)
; #define PG8_MMA(ai, bj, At, Bt) do { __builtin_amdgcn_s_setprio(1); _Pragma("unroll") for (int m = 0; m < 4; ++m) _Pragma("unroll") for (int n = 0; n < 2; ++n) _Pragma("unroll") for (int k = 0; k < 2; ++k) \
;         acc[ai][bj][m][n] = __builtin_amdgcn_mfma_f32_16x16x32_bf16(Bt[n][k], At[m][k], acc[ai][bj][m][n], 0, 0, 0); __builtin_amdgcn_s_setprio(0); } while (0)
; #define PG8_WAIT_V(n) asm volatile("s_waitcnt vmcnt(" #n ")" ::: "memory")
; #define PG8_WAIT_L(n) asm volatile("s_waitcnt lgkmcnt(" #n ")" ::: "memory")
; #define PG8_BAR __builtin_amdgcn_s_barrier()
; #define PG8_SCHED __builtin_amdgcn_sched_barrier(0)
; template <class Epi, class Sched, bool ALIGN_EPI = false, bool SP2 = false>
; __device__ __forceinline__ void gemm_phase(PG8_LAS unsigned char* lds, const Gemm g, const Sched& S, const Epi& E, const int wv) {
;     ...
;             PG8_WAIT_V(8); PG8_WAIT_L(0); PG8_BAR; PG8_MMA(1, 0, At, B0); PG8_MMA(1, 1, At, B1); PG8_BAR; PG8_SCHED;
;             PG8_LDB(B0, 1, 0); PG8_LDB(B1, 1, 1); PG8_SCHED; PG8_LDA(At, 1, 0); PG8_STAGE(PG8_SA(0, 1), a2 + hstep, voffA);
;             PG8_WAIT_V(8); PG8_WAIT_L(0); PG8_BAR; PG8_MMA(0, 0, At, B0); PG8_MMA(0, 1, At, B1); PG8_BAR; PG8_SCHED;
	s_waitcnt lgkmcnt(0)
	v_mfma_f32_16x16x32_bf16 v[62:65], v[140:143], v[178:181], v[62:65]
	v_mfma_f32_16x16x32_bf16 v[54:57], v[148:151], v[178:181], v[54:57]
	v_mfma_f32_16x16x32_bf16 v[46:49], v[140:143], v[186:189], v[46:49]
	v_mfma_f32_16x16x32_bf16 v[38:41], v[148:151], v[186:189], v[38:41]
	v_mfma_f32_16x16x32_bf16 v[30:33], v[140:143], v[194:197], v[30:33]
	v_mfma_f32_16x16x32_bf16 v[22:25], v[148:151], v[194:197], v[22:25]
	v_mfma_f32_16x16x32_bf16 v[14:17], v[140:143], v[202:205], v[14:17]
	v_mfma_f32_16x16x32_bf16 v[6:9], v[148:151], v[202:205], v[6:9]
	v_mfma_f32_16x16x32_bf16 v[62:65], v[144:147], v[182:185], v[62:65]
	v_mfma_f32_16x16x32_bf16 v[54:57], v[152:155], v[182:185], v[54:57]
	v_mfma_f32_16x16x32_bf16 v[46:49], v[144:147], v[190:193], v[46:49]
	v_mfma_f32_16x16x32_bf16 v[38:41], v[152:155], v[190:193], v[38:41]
	v_mfma_f32_16x16x32_bf16 v[30:33], v[144:147], v[198:201], v[30:33]
	v_mfma_f32_16x16x32_bf16 v[22:25], v[152:155], v[198:201], v[22:25]
	v_mfma_f32_16x16x32_bf16 v[14:17], v[144:147], v[206:209], v[14:17]
	v_mfma_f32_16x16x32_bf16 v[6:9], v[152:155], v[206:209], v[6:9]
	s_setprio 0
	s_setprio 1
	v_mfma_f32_16x16x32_bf16 v[58:61], v[156:159], v[178:181], v[58:61]
	v_mfma_f32_16x16x32_bf16 v[50:53], v[170:173], v[178:181], v[50:53]
	v_mfma_f32_16x16x32_bf16 v[42:45], v[156:159], v[186:189], v[42:45]
	v_mfma_f32_16x16x32_bf16 v[34:37], v[170:173], v[186:189], v[34:37]
	v_mfma_f32_16x16x32_bf16 v[26:29], v[156:159], v[194:197], v[26:29]
	v_mfma_f32_16x16x32_bf16 v[18:21], v[170:173], v[194:197], v[18:21]
	v_mfma_f32_16x16x32_bf16 v[10:13], v[156:159], v[202:205], v[10:13]
	v_mfma_f32_16x16x32_bf16 v[2:5], v[170:173], v[202:205], v[2:5]
	v_mfma_f32_16x16x32_bf16 v[58:61], v[160:163], v[182:185], v[58:61]
	v_mfma_f32_16x16x32_bf16 v[50:53], v[174:177], v[182:185], v[50:53]
	v_mfma_f32_16x16x32_bf16 v[42:45], v[160:163], v[190:193], v[42:45]
	v_mfma_f32_16x16x32_bf16 v[34:37], v[174:177], v[190:193], v[34:37]
	v_mfma_f32_16x16x32_bf16 v[26:29], v[160:163], v[198:201], v[26:29]
	v_mfma_f32_16x16x32_bf16 v[18:21], v[174:177], v[198:201], v[18:21]
	v_mfma_f32_16x16x32_bf16 v[10:13], v[160:163], v[206:209], v[10:13]
	v_mfma_f32_16x16x32_bf16 v[2:5], v[174:177], v[206:209], v[2:5]
	s_barrier
	s_setprio 0
	s_add_i32 s46, 0, 0x18000
	s_add_i32 s47, 0, 0x1c000
	v_add_u32_e32 v152, s46, v166
	v_add_u32_e32 v164, s47, v166
	ds_read_b128 v[140:143], v152
	ds_read_b128 v[144:147], v152 offset:1024
	ds_read_b128 v[148:151], v152 offset:2048
	ds_read_b128 v[152:155], v152 offset:3072
	ds_read_b128 v[156:159], v164
	ds_read_b128 v[160:163], v164 offset:1024
	ds_read_b128 v[170:173], v164 offset:2048
	ds_read_b128 v[174:177], v164 offset:3072
	s_add_u32 s22, s22, 0x40000
	s_addc_u32 s23, s23, 0
	s_mov_b32 m0, s36
	v_lshl_add_u64 v[218:219], s[22:23], 0, v[134:135]
	ds_read_b128 v[178:181], v168 offset:32768
	ds_read_b128 v[182:185], v168 offset:33792
	ds_read_b128 v[186:189], v168 offset:34816
	ds_read_b128 v[190:193], v168 offset:35840
	ds_read_b128 v[194:197], v168 offset:36864
	ds_read_b128 v[198:201], v168 offset:37888
	ds_read_b128 v[202:205], v168 offset:38912
	ds_read_b128 v[206:209], v168 offset:39936
	global_load_lds_dwordx4 v[218:219], off
	v_lshl_add_u64 v[218:219], s[22:23], 0, v[132:133]
	s_mov_b32 m0, s37
	s_nop 0
	global_load_lds_dwordx4 v[218:219], off
	s_waitcnt vmcnt(8)
	s_waitcnt lgkmcnt(0)
	s_setprio 1
	s_barrier
	s_waitcnt lgkmcnt(0)
	v_mfma_f32_16x16x32_bf16 v[126:129], v[140:143], v[178:181], v[126:129]
	v_mfma_f32_16x16x32_bf16 v[118:121], v[148:151], v[178:181], v[118:121]
	v_mfma_f32_16x16x32_bf16 v[110:113], v[140:143], v[186:189], v[110:113]
	v_mfma_f32_16x16x32_bf16 v[102:105], v[148:151], v[186:189], v[102:105]
	v_mfma_f32_16x16x32_bf16 v[94:97], v[140:143], v[194:197], v[94:97]
	v_mfma_f32_16x16x32_bf16 v[86:89], v[148:151], v[194:197], v[86:89]
	v_mfma_f32_16x16x32_bf16 v[78:81], v[140:143], v[202:205], v[78:81]
	v_mfma_f32_16x16x32_bf16 v[70:73], v[148:151], v[202:205], v[70:73]
	v_mfma_f32_16x16x32_bf16 v[126:129], v[144:147], v[182:185], v[126:129]
	v_mfma_f32_16x16x32_bf16 v[118:121], v[152:155], v[182:185], v[118:121]
	v_mfma_f32_16x16x32_bf16 v[110:113], v[144:147], v[190:193], v[110:113]
	v_mfma_f32_16x16x32_bf16 v[102:105], v[152:155], v[190:193], v[102:105]
	v_mfma_f32_16x16x32_bf16 v[94:97], v[144:147], v[198:201], v[94:97]
	v_mfma_f32_16x16x32_bf16 v[86:89], v[152:155], v[198:201], v[86:89]
	v_mfma_f32_16x16x32_bf16 v[78:81], v[144:147], v[206:209], v[78:81]
	v_mfma_f32_16x16x32_bf16 v[70:73], v[152:155], v[206:209], v[70:73]
	s_setprio 0
	s_setprio 1
	v_mfma_f32_16x16x32_bf16 v[122:125], v[156:159], v[178:181], v[122:125]
	v_mfma_f32_16x16x32_bf16 v[114:117], v[170:173], v[178:181], v[114:117]
	v_mfma_f32_16x16x32_bf16 v[106:109], v[156:159], v[186:189], v[106:109]
	v_mfma_f32_16x16x32_bf16 v[98:101], v[170:173], v[186:189], v[98:101]
	v_mfma_f32_16x16x32_bf16 v[90:93], v[156:159], v[194:197], v[90:93]
	v_mfma_f32_16x16x32_bf16 v[82:85], v[170:173], v[194:197], v[82:85]
	v_mfma_f32_16x16x32_bf16 v[74:77], v[156:159], v[202:205], v[74:77]
	v_mfma_f32_16x16x32_bf16 v[66:69], v[170:173], v[202:205], v[66:69]
	v_mfma_f32_16x16x32_bf16 v[122:125], v[160:163], v[182:185], v[122:125]
	v_mfma_f32_16x16x32_bf16 v[114:117], v[174:177], v[182:185], v[114:117]
	v_mfma_f32_16x16x32_bf16 v[106:109], v[160:163], v[190:193], v[106:109]
	v_mfma_f32_16x16x32_bf16 v[98:101], v[174:177], v[190:193], v[98:101]
	v_mfma_f32_16x16x32_bf16 v[90:93], v[160:163], v[198:201], v[90:93]
	v_mfma_f32_16x16x32_bf16 v[82:85], v[174:177], v[198:201], v[82:85]
	v_mfma_f32_16x16x32_bf16 v[74:77], v[160:163], v[206:209], v[74:77]
	v_mfma_f32_16x16x32_bf16 v[66:69], v[174:177], v[206:209], v[66:69]
	s_barrier
; #define PG8_STAGE(bufoff, gbase, voff) do { _Pragma("unroll") for (int _i = 0; _i < 2; ++_i) \
;         __builtin_amdgcn_global_load_lds((const unsigned*)((const char*)(gbase) + (voff)[_i]), (PG8_LAS unsigned*)(lds + (bufoff) + ldsw + _i * 8192), 16, 0, 0); } while (0)
; #define PG8_LDA(dst, b, h) do { _Pragma("unroll") for (int m = 0; m < 4; ++m) _Pragma("unroll") for (int k = 0; k < 2; ++k) dst[m][k] = *(const PG8_LAS bf16x8*)(lds + PG8_SA(b, h) + aoff + m * 2048 + k * 1024); } while (0)
; #define PG8_MMA(ai, bj, At, Bt) do { __builtin_amdgcn_s_setprio(1); _Pragma("unroll") for (int m = 0; m < 4; ++m) _Pragma("unroll") for (int n = 0; n < 2; ++n) _Pragma("unroll") for (int k = 0; k < 2; ++k) \
;         acc[ai][bj][m][n] = __builtin_amdgcn_mfma_f32_16x16x32_bf16(Bt[n][k], At[m][k], acc[ai][bj][m][n], 0, 0, 0); __builtin_amdgcn_s_setprio(0); } while (0)
; #define PG8_WAIT_V(n) asm volatile("s_waitcnt vmcnt(" #n ")" ::: "memory")
; #define PG8_WAIT_L(n) asm volatile("s_waitcnt lgkmcnt(" #n ")" ::: "memory")
; #define PG8_BAR __builtin_amdgcn_s_barrier()
; #define PG8_SCHED __builtin_amdgcn_sched_barrier(0)
; template <class Epi, class Sched, bool ALIGN_EPI = false, bool SP2 = false>
; __device__ __forceinline__ void gemm_phase(PG8_LAS unsigned char* lds, const Gemm g, const Sched& S, const Epi& E, const int wv) {
;     ...
;             PG8_LDA(At, 1, 1); PG8_STAGE(PG8_SB(1, 0), b3, voffB); PG8_STAGE(PG8_SB(1, 1), b3 + hstep, voffB); PG8_STAGE(PG8_SA(1, 0), a3, voffA);
;             PG8_WAIT_V(8); PG8_WAIT_L(0); PG8_BAR; PG8_MMA(1, 0, At, B0); PG8_MMA(1, 1, At, B1); PG8_BAR; PG8_SCHED;
	s_setprio 0
	ds_read_b128 v[178:181], v168 offset:49152
	ds_read_b128 v[182:185], v168 offset:50176
	ds_read_b128 v[186:189], v168 offset:51200
	ds_read_b128 v[190:193], v168 offset:52224
	ds_read_b128 v[194:197], v168 offset:53248
	ds_read_b128 v[198:201], v168 offset:54272
	ds_read_b128 v[202:205], v168 offset:55296
	ds_read_b128 v[206:209], v168 offset:56320
	s_add_i32 s22, s46, s29
	v_lshl_add_u64 v[210:211], v[210:211], 0, s[2:3]
	s_mov_b32 m0, s22
	global_load_lds_dwordx4 v[210:211], off
	s_add_i32 m0, s22, 0x2000
	s_add_u32 s20, s20, 0x40080
	v_lshl_add_u64 v[210:211], v[212:213], 0, s[2:3]
	s_addc_u32 s21, s21, 0
	s_add_i32 s22, s47, s29
	global_load_lds_dwordx4 v[210:211], off
	v_lshl_add_u64 v[210:211], s[20:21], 0, v[0:1]
	s_mov_b32 m0, s22
	s_nop 0
	global_load_lds_dwordx4 v[210:211], off
	v_lshl_add_u64 v[210:211], s[20:21], 0, v[130:131]
	s_add_i32 m0, s22, 0x2000
	s_nop 0
	global_load_lds_dwordx4 v[210:211], off
	v_lshl_add_u64 v[210:211], v[214:215], 0, s[2:3]
	s_mov_b32 m0, s39
	s_nop 0
	global_load_lds_dwordx4 v[210:211], off
	v_lshl_add_u64 v[210:211], v[216:217], 0, s[2:3]
	s_mov_b32 m0, s40
	s_nop 0
	global_load_lds_dwordx4 v[210:211], off
	s_waitcnt vmcnt(8)
	s_waitcnt lgkmcnt(0)
	s_setprio 1
	s_barrier
	s_waitcnt lgkmcnt(0)
	v_mfma_f32_16x16x32_bf16 v[62:65], v[140:143], v[178:181], v[62:65]
	v_mfma_f32_16x16x32_bf16 v[54:57], v[148:151], v[178:181], v[54:57]
	v_mfma_f32_16x16x32_bf16 v[46:49], v[140:143], v[186:189], v[46:49]
	v_mfma_f32_16x16x32_bf16 v[38:41], v[148:151], v[186:189], v[38:41]
	v_mfma_f32_16x16x32_bf16 v[30:33], v[140:143], v[194:197], v[30:33]
	v_mfma_f32_16x16x32_bf16 v[22:25], v[148:151], v[194:197], v[22:25]
	v_mfma_f32_16x16x32_bf16 v[14:17], v[140:143], v[202:205], v[14:17]
	v_mfma_f32_16x16x32_bf16 v[6:9], v[148:151], v[202:205], v[6:9]
	v_mfma_f32_16x16x32_bf16 v[62:65], v[144:147], v[182:185], v[62:65]
	v_mfma_f32_16x16x32_bf16 v[54:57], v[152:155], v[182:185], v[54:57]
	v_mfma_f32_16x16x32_bf16 v[46:49], v[144:147], v[190:193], v[46:49]
	v_mfma_f32_16x16x32_bf16 v[38:41], v[152:155], v[190:193], v[38:41]
	v_mfma_f32_16x16x32_bf16 v[30:33], v[144:147], v[198:201], v[30:33]
	v_mfma_f32_16x16x32_bf16 v[22:25], v[152:155], v[198:201], v[22:25]
	v_mfma_f32_16x16x32_bf16 v[14:17], v[144:147], v[206:209], v[14:17]
	v_mfma_f32_16x16x32_bf16 v[6:9], v[152:155], v[206:209], v[6:9]
	s_setprio 0
	s_setprio 1
	v_mfma_f32_16x16x32_bf16 v[58:61], v[156:159], v[178:181], v[58:61]
	v_mfma_f32_16x16x32_bf16 v[50:53], v[170:173], v[178:181], v[50:53]
	v_mfma_f32_16x16x32_bf16 v[42:45], v[156:159], v[186:189], v[42:45]
	v_mfma_f32_16x16x32_bf16 v[34:37], v[170:173], v[186:189], v[34:37]
	v_mfma_f32_16x16x32_bf16 v[26:29], v[156:159], v[194:197], v[26:29]
	v_mfma_f32_16x16x32_bf16 v[18:21], v[170:173], v[194:197], v[18:21]
	v_mfma_f32_16x16x32_bf16 v[10:13], v[156:159], v[202:205], v[10:13]
	v_mfma_f32_16x16x32_bf16 v[2:5], v[170:173], v[202:205], v[2:5]
	v_mfma_f32_16x16x32_bf16 v[58:61], v[160:163], v[182:185], v[58:61]
	v_mfma_f32_16x16x32_bf16 v[50:53], v[174:177], v[182:185], v[50:53]
	v_mfma_f32_16x16x32_bf16 v[42:45], v[160:163], v[190:193], v[42:45]
	v_mfma_f32_16x16x32_bf16 v[34:37], v[174:177], v[190:193], v[34:37]
	v_mfma_f32_16x16x32_bf16 v[26:29], v[160:163], v[198:201], v[26:29]
	v_mfma_f32_16x16x32_bf16 v[18:21], v[174:177], v[198:201], v[18:21]
	v_mfma_f32_16x16x32_bf16 v[10:13], v[160:163], v[206:209], v[10:13]
	v_mfma_f32_16x16x32_bf16 v[2:5], v[174:177], v[206:209], v[2:5]
	s_barrier
	s_setprio 0
	s_add_i32 s45, s45, 2
	s_add_u32 s18, s18, 0x100
	s_addc_u32 s19, s19, 0
	s_add_u32 s43, s43, 0x100
	s_addc_u32 s44, s44, 0
	s_cmp_gt_u32 s45, 13
	s_cbranch_scc0 .LBB0_428
	s_and_b64 vcc, exec, s[6:7]
	s_cbranch_vccz .LBB0_431
	s_barrier

; #define PG8_STAGE(bufoff, gbase, voff) do { _Pragma("unroll") for (int _i = 0; _i < 2; ++_i) \
;         __builtin_amdgcn_global_load_lds((const unsigned*)((const char*)(gbase) + (voff)[_i]), (PG8_LAS unsigned*)(lds + (bufoff) + ldsw + _i * 8192), 16, 0, 0); } while (0)
; #define PG8_LDA(dst, b, h) do { _Pragma("unroll") for (int m = 0; m < 4; ++m) _Pragma("unroll") for (int k = 0; k < 2; ++k) dst[m][k] = *(const PG8_LAS bf16x8*)(lds + PG8_SA(b, h) + aoff + m * 2048 + k * 1024); } while (0)
; #define PG8_LDB(dst, b, h) do { _Pragma("unroll") for (int n = 0; n < 2; ++n) _Pragma("unroll") for (int k = 0; k < 2; ++k) dst[n][k] = *(const PG8_LAS bf16x8*)(lds + PG8_SB(b, h) + boff + n * 2048 + k * 1024); } while (0)
; #define PG8_MMA(ai, bj, At, Bt) do { __builtin_amdgcn_s_setprio(1); _Pragma("unroll") for (int m = 0; m < 4; ++m) _Pragma("unroll") for (int n = 0; n < 2; ++n) _Pragma("unroll") for (int k = 0; k < 2; ++k) \
;         acc[ai][bj][m][n] = __builtin_amdgcn_mfma_f32_16x16x32_bf16(Bt[n][k], At[m][k], acc[ai][bj][m][n], 0, 0, 0); __builtin_amdgcn_s_setprio(0); } while (0)
; #define PG8_WAIT_V(n) asm volatile("s_waitcnt vmcnt(" #n ")" ::: "memory")
; #define PG8_WAIT_L(n) asm volatile("s_waitcnt lgkmcnt(" #n ")" ::: "memory")
; #define PG8_BAR __builtin_amdgcn_s_barrier()
; #define PG8_SCHED __builtin_amdgcn_sched_barrier(0)
; template <class Epi, class Sched, bool ALIGN_EPI = false, bool SP2 = false>
; __device__ __forceinline__ void gemm_phase(PG8_LAS unsigned char* lds, const Gemm g, const Sched& S, const Epi& E, const int wv) {
;     ...
;             const bool last = (t == nt - 2);
;             const char* a1 = cA + (size_t)(t + 1) * kstep;
;             const char* a2 = last ? nA : cA + (size_t)(t + 2) * kstep; const char* b2 = last ? nB : cB + (size_t)(t + 2) * kstep;
;             const char* a3 = a2 + kstep; const char* b3 = b2 + kstep;
;             if (last && has_next) S.a_ready(nxt);
;             if constexpr (SP2) {
;             PG8_LDB(B0, 0, 0); PG8_LDB(B1, 0, 1); PG8_SCHED; PG8_LDA(At, 0, 0); PG8_STAGE(PG8_SA(1, 1), a1 + hstep, voffA);
;             PG8_WAIT_V(8); PG8_WAIT_L(0); PG8_BAR; PG8_MMA(0, 0, At, B0); PG8_MMA(0, 1, At, B1); PG8_BAR; PG8_SCHED;
;             PG8_LDA(At, 0, 1); PG8_STAGE(PG8_SB(0, 0), b2, voffB); PG8_STAGE(PG8_SB(0, 1), b2 + hstep, voffB); PG8_STAGE(PG8_SA(0, 0), a2, voffA);
.LBB0_504:
	s_add_u32 s10, s8, 0x100
	s_addc_u32 s11, s9, 0
	s_add_i32 s52, 0, 0x10000
	s_cmp_eq_u32 s51, 40
	s_cselect_b32 s29, s1, s11
	s_cselect_b32 s28, s0, s10
	s_cselect_b32 s27, s25, s50
	s_cselect_b32 s26, s24, s49
	s_add_i32 s53, 0, 0x14000
	v_add_u32_e32 v142, s52, v187
	v_add_u32_e32 v168, s53, v187
	ds_read_b128 v[122:125], v142
	ds_read_b128 v[130:133], v142 offset:1024
	ds_read_b128 v[138:141], v142 offset:2048
	ds_read_b128 v[142:145], v142 offset:3072
	ds_read_b128 v[146:149], v168
	ds_read_b128 v[150:153], v168 offset:1024
	ds_read_b128 v[154:157], v168 offset:2048
	ds_read_b128 v[168:171], v168 offset:3072
	v_lshl_add_u64 v[184:185], s[8:9], 0, v[164:165]
	s_add_i32 m0, s37, 0xc000
	ds_read_b128 v[172:175], v189
	ds_read_b128 v[176:179], v189 offset:1024
	ds_read_b128 v[180:183], v189 offset:2048
	ds_read_b128 v[190:193], v189 offset:3072
	ds_read_b128 v[194:197], v189 offset:4096
	ds_read_b128 v[198:201], v189 offset:5120
	ds_read_b128 v[202:205], v189 offset:6144
	ds_read_b128 v[206:209], v189 offset:7168
	global_load_lds_dwordx4 v[184:185], off
	v_lshl_add_u64 v[184:185], s[8:9], 0, v[166:167]
	s_add_i32 m0, s37, 0xe000
	s_nop 0
	global_load_lds_dwordx4 v[184:185], off
	s_waitcnt vmcnt(8)
	s_waitcnt lgkmcnt(0)
	s_setprio 1
	s_barrier
	s_waitcnt lgkmcnt(0)
	v_mfma_f32_16x16x32_bf16 v[134:137], v[122:125], v[172:175], v[134:137]
	v_mfma_f32_16x16x32_bf16 v[126:129], v[138:141], v[172:175], v[126:129]
	v_mfma_f32_16x16x32_bf16 v[110:113], v[122:125], v[180:183], v[110:113]
	v_mfma_f32_16x16x32_bf16 v[106:109], v[138:141], v[180:183], v[106:109]
	v_mfma_f32_16x16x32_bf16 v[94:97], v[122:125], v[194:197], v[94:97]
	v_mfma_f32_16x16x32_bf16 v[90:93], v[138:141], v[194:197], v[90:93]
	v_mfma_f32_16x16x32_bf16 v[78:81], v[122:125], v[202:205], v[78:81]
	v_mfma_f32_16x16x32_bf16 v[74:77], v[138:141], v[202:205], v[74:77]
	v_mfma_f32_16x16x32_bf16 v[134:137], v[130:133], v[176:179], v[134:137]
	v_mfma_f32_16x16x32_bf16 v[126:129], v[142:145], v[176:179], v[126:129]
	v_mfma_f32_16x16x32_bf16 v[110:113], v[130:133], v[190:193], v[110:113]
	v_mfma_f32_16x16x32_bf16 v[106:109], v[142:145], v[190:193], v[106:109]
	v_mfma_f32_16x16x32_bf16 v[94:97], v[130:133], v[198:201], v[94:97]
	v_mfma_f32_16x16x32_bf16 v[90:93], v[142:145], v[198:201], v[90:93]
	v_mfma_f32_16x16x32_bf16 v[78:81], v[130:133], v[206:209], v[78:81]
	v_mfma_f32_16x16x32_bf16 v[74:77], v[142:145], v[206:209], v[74:77]
	s_setprio 0
	s_setprio 1
	v_mfma_f32_16x16x32_bf16 v[118:121], v[146:149], v[172:175], v[118:121]
	v_mfma_f32_16x16x32_bf16 v[114:117], v[154:157], v[172:175], v[114:117]
	v_mfma_f32_16x16x32_bf16 v[102:105], v[146:149], v[180:183], v[102:105]
	v_mfma_f32_16x16x32_bf16 v[98:101], v[154:157], v[180:183], v[98:101]
	v_mfma_f32_16x16x32_bf16 v[86:89], v[146:149], v[194:197], v[86:89]
	v_mfma_f32_16x16x32_bf16 v[82:85], v[154:157], v[194:197], v[82:85]
	v_mfma_f32_16x16x32_bf16 v[70:73], v[146:149], v[202:205], v[70:73]
	v_mfma_f32_16x16x32_bf16 v[66:69], v[154:157], v[202:205], v[66:69]
	v_mfma_f32_16x16x32_bf16 v[118:121], v[150:153], v[176:179], v[118:121]
	v_mfma_f32_16x16x32_bf16 v[114:117], v[168:171], v[176:179], v[114:117]
	v_mfma_f32_16x16x32_bf16 v[102:105], v[150:153], v[190:193], v[102:105]
	v_mfma_f32_16x16x32_bf16 v[98:101], v[168:171], v[190:193], v[98:101]
	v_mfma_f32_16x16x32_bf16 v[86:89], v[150:153], v[198:201], v[86:89]
	v_mfma_f32_16x16x32_bf16 v[82:85], v[168:171], v[198:201], v[82:85]
	v_mfma_f32_16x16x32_bf16 v[70:73], v[150:153], v[206:209], v[70:73]
	v_mfma_f32_16x16x32_bf16 v[66:69], v[168:171], v[206:209], v[66:69]
	s_barrier
	s_setprio 0
	ds_read_b128 v[172:175], v189 offset:16384
	ds_read_b128 v[176:179], v189 offset:17408
	ds_read_b128 v[180:183], v189 offset:18432
	ds_read_b128 v[190:193], v189 offset:19456
	ds_read_b128 v[194:197], v189 offset:20480
	ds_read_b128 v[198:201], v189 offset:21504
	ds_read_b128 v[202:205], v189 offset:22528
	ds_read_b128 v[206:209], v189 offset:23552
	s_add_i32 s8, s52, s36
	v_lshl_add_u64 v[184:185], s[26:27], 0, v[0:1]
	s_mov_b32 m0, s8
	global_load_lds_dwordx4 v[184:185], off
	s_add_i32 m0, s8, 0x2000
	s_add_u32 s8, s26, 0xb0000
	v_lshl_add_u64 v[210:211], s[26:27], 0, v[162:163]
	s_addc_u32 s9, s27, 0
	s_add_i32 s52, s53, s36
	global_load_lds_dwordx4 v[210:211], off
	v_lshl_add_u64 v[212:213], s[8:9], 0, v[0:1]
	s_mov_b32 m0, s52
	v_lshl_add_u64 v[214:215], s[28:29], 0, v[160:161]
	global_load_lds_dwordx4 v[212:213], off
	v_lshl_add_u64 v[212:213], s[8:9], 0, v[162:163]
	s_add_i32 m0, s52, 0x2000
	s_nop 0
	global_load_lds_dwordx4 v[212:213], off
	v_lshl_add_u64 v[212:213], s[28:29], 0, v[158:159]
	s_mov_b32 m0, s37
	s_nop 0
	global_load_lds_dwordx4 v[212:213], off
	s_mov_b32 m0, s38
	s_nop 0
	global_load_lds_dwordx4 v[214:215], off
	s_waitcnt vmcnt(8)
	s_waitcnt lgkmcnt(0)
	s_setprio 1
	s_barrier
; #define PG8_STAGE(bufoff, gbase, voff) do { _Pragma("unroll") for (int _i = 0; _i < 2; ++_i) \
;         __builtin_amdgcn_global_load_lds((const unsigned*)((const char*)(gbase) + (voff)[_i]), (PG8_LAS unsigned*)(lds + (bufoff) + ldsw + _i * 8192), 16, 0, 0); } while (0)
; #define PG8_LDA(dst, b, h) do { _Pragma("unroll") for (int m = 0; m < 4; ++m) _Pragma("unroll") for (int k = 0; k < 2; ++k) dst[m][k] = *(const PG8_LAS bf16x8*)(lds + PG8_SA(b, h) + aoff + m * 2048 + k * 1024); } while (0)
; #define PG8_LDB(dst, b, h) do { _Pragma("unroll") for (int n = 0; n < 2; ++n) _Pragma("unroll") for (int k = 0; k < 2; ++k) dst[n][k] = *(const PG8_LAS bf16x8*)(lds + PG8_SB(b, h) + boff + n * 2048 + k * 1024); } while (0)
; #define PG8_MMA(ai, bj, At, Bt) do { __builtin_amdgcn_s_setprio(1); _Pragma("unroll") for (int m = 0; m < 4; ++m) _Pragma("unroll") for (int n = 0; n < 2; ++n) _Pragma("unroll") for (int k = 0; k < 2; ++k) \
;         acc[ai][bj][m][n] = __builtin_amdgcn_mfma_f32_16x16x32_bf16(Bt[n][k], At[m][k], acc[ai][bj][m][n], 0, 0, 0); __builtin_amdgcn_s_setprio(0); } while (0)
; #define PG8_WAIT_V(n) asm volatile("s_waitcnt vmcnt(" #n ")" ::: "memory")
; #define PG8_WAIT_L(n) asm volatile("s_waitcnt lgkmcnt(" #n ")" ::: "memory")
; #define PG8_BAR __builtin_amdgcn_s_barrier()
; #define PG8_SCHED __builtin_amdgcn_sched_barrier(0)
; template <class Epi, class Sched, bool ALIGN_EPI = false, bool SP2 = false>
; __device__ __forceinline__ void gemm_phase(PG8_LAS unsigned char* lds, const Gemm g, const Sched& S, const Epi& E, const int wv) {
;     ...
;             PG8_WAIT_V(8); PG8_WAIT_L(0); PG8_BAR; PG8_MMA(1, 0, At, B0); PG8_MMA(1, 1, At, B1); PG8_BAR; PG8_SCHED;
;             PG8_LDB(B0, 1, 0); PG8_LDB(B1, 1, 1); PG8_SCHED; PG8_LDA(At, 1, 0); PG8_STAGE(PG8_SA(0, 1), a2 + hstep, voffA);
;             PG8_WAIT_V(8); PG8_WAIT_L(0); PG8_BAR; PG8_MMA(0, 0, At, B0); PG8_MMA(0, 1, At, B1); PG8_BAR; PG8_SCHED;
	s_waitcnt lgkmcnt(0)
	v_mfma_f32_16x16x32_bf16 v[62:65], v[122:125], v[172:175], v[62:65]
	v_mfma_f32_16x16x32_bf16 v[58:61], v[138:141], v[172:175], v[58:61]
	v_mfma_f32_16x16x32_bf16 v[46:49], v[122:125], v[180:183], v[46:49]
	v_mfma_f32_16x16x32_bf16 v[42:45], v[138:141], v[180:183], v[42:45]
	v_mfma_f32_16x16x32_bf16 v[30:33], v[122:125], v[194:197], v[30:33]
	v_mfma_f32_16x16x32_bf16 v[26:29], v[138:141], v[194:197], v[26:29]
	v_mfma_f32_16x16x32_bf16 v[14:17], v[122:125], v[202:205], v[14:17]
	v_mfma_f32_16x16x32_bf16 v[10:13], v[138:141], v[202:205], v[10:13]
	v_mfma_f32_16x16x32_bf16 v[62:65], v[130:133], v[176:179], v[62:65]
	v_mfma_f32_16x16x32_bf16 v[58:61], v[142:145], v[176:179], v[58:61]
	v_mfma_f32_16x16x32_bf16 v[46:49], v[130:133], v[190:193], v[46:49]
	v_mfma_f32_16x16x32_bf16 v[42:45], v[142:145], v[190:193], v[42:45]
	v_mfma_f32_16x16x32_bf16 v[30:33], v[130:133], v[198:201], v[30:33]
	v_mfma_f32_16x16x32_bf16 v[26:29], v[142:145], v[198:201], v[26:29]
	v_mfma_f32_16x16x32_bf16 v[14:17], v[130:133], v[206:209], v[14:17]
	v_mfma_f32_16x16x32_bf16 v[10:13], v[142:145], v[206:209], v[10:13]
	s_setprio 0
	s_setprio 1
	v_mfma_f32_16x16x32_bf16 v[54:57], v[146:149], v[172:175], v[54:57]
	v_mfma_f32_16x16x32_bf16 v[50:53], v[154:157], v[172:175], v[50:53]
	v_mfma_f32_16x16x32_bf16 v[38:41], v[146:149], v[180:183], v[38:41]
	v_mfma_f32_16x16x32_bf16 v[34:37], v[154:157], v[180:183], v[34:37]
	v_mfma_f32_16x16x32_bf16 v[22:25], v[146:149], v[194:197], v[22:25]
	v_mfma_f32_16x16x32_bf16 v[18:21], v[154:157], v[194:197], v[18:21]
	v_mfma_f32_16x16x32_bf16 v[6:9], v[146:149], v[202:205], v[6:9]
	v_mfma_f32_16x16x32_bf16 v[2:5], v[154:157], v[202:205], v[2:5]
	v_mfma_f32_16x16x32_bf16 v[54:57], v[150:153], v[176:179], v[54:57]
	v_mfma_f32_16x16x32_bf16 v[50:53], v[168:171], v[176:179], v[50:53]
	v_mfma_f32_16x16x32_bf16 v[38:41], v[150:153], v[190:193], v[38:41]
	v_mfma_f32_16x16x32_bf16 v[34:37], v[168:171], v[190:193], v[34:37]
	v_mfma_f32_16x16x32_bf16 v[22:25], v[150:153], v[198:201], v[22:25]
	v_mfma_f32_16x16x32_bf16 v[18:21], v[168:171], v[198:201], v[18:21]
	v_mfma_f32_16x16x32_bf16 v[6:9], v[150:153], v[206:209], v[6:9]
	v_mfma_f32_16x16x32_bf16 v[2:5], v[168:171], v[206:209], v[2:5]
	s_barrier
	s_setprio 0
	s_add_i32 s52, 0, 0x18000
	s_add_i32 s53, 0, 0x1c000
	v_add_u32_e32 v142, s52, v187
	v_add_u32_e32 v168, s53, v187
	ds_read_b128 v[122:125], v142
	ds_read_b128 v[130:133], v142 offset:1024
	ds_read_b128 v[138:141], v142 offset:2048
	ds_read_b128 v[142:145], v142 offset:3072
	ds_read_b128 v[146:149], v168
	ds_read_b128 v[150:153], v168 offset:1024
	ds_read_b128 v[154:157], v168 offset:2048
	ds_read_b128 v[168:171], v168 offset:3072
	s_add_u32 s8, s28, 0xb0000
	s_addc_u32 s9, s29, 0
	s_mov_b32 m0, s39
	v_lshl_add_u64 v[216:217], s[8:9], 0, v[158:159]
	ds_read_b128 v[172:175], v189 offset:32768
	ds_read_b128 v[176:179], v189 offset:33792
	ds_read_b128 v[180:183], v189 offset:34816
	ds_read_b128 v[190:193], v189 offset:35840
	ds_read_b128 v[194:197], v189 offset:36864
	ds_read_b128 v[198:201], v189 offset:37888
	ds_read_b128 v[202:205], v189 offset:38912
	ds_read_b128 v[206:209], v189 offset:39936
	global_load_lds_dwordx4 v[216:217], off
	v_lshl_add_u64 v[216:217], s[8:9], 0, v[160:161]
	s_mov_b32 m0, s40
	s_nop 0
	global_load_lds_dwordx4 v[216:217], off
	s_waitcnt vmcnt(8)
	s_waitcnt lgkmcnt(0)
	s_setprio 1
	s_barrier
	s_waitcnt lgkmcnt(0)
	v_mfma_f32_16x16x32_bf16 v[134:137], v[122:125], v[172:175], v[134:137]
	v_mfma_f32_16x16x32_bf16 v[126:129], v[138:141], v[172:175], v[126:129]
	v_mfma_f32_16x16x32_bf16 v[110:113], v[122:125], v[180:183], v[110:113]
	v_mfma_f32_16x16x32_bf16 v[106:109], v[138:141], v[180:183], v[106:109]
	v_mfma_f32_16x16x32_bf16 v[94:97], v[122:125], v[194:197], v[94:97]
	v_mfma_f32_16x16x32_bf16 v[90:93], v[138:141], v[194:197], v[90:93]
	v_mfma_f32_16x16x32_bf16 v[78:81], v[122:125], v[202:205], v[78:81]
	v_mfma_f32_16x16x32_bf16 v[74:77], v[138:141], v[202:205], v[74:77]
	v_mfma_f32_16x16x32_bf16 v[134:137], v[130:133], v[176:179], v[134:137]
	v_mfma_f32_16x16x32_bf16 v[126:129], v[142:145], v[176:179], v[126:129]
	v_mfma_f32_16x16x32_bf16 v[110:113], v[130:133], v[190:193], v[110:113]
	v_mfma_f32_16x16x32_bf16 v[106:109], v[142:145], v[190:193], v[106:109]
	v_mfma_f32_16x16x32_bf16 v[94:97], v[130:133], v[198:201], v[94:97]
	v_mfma_f32_16x16x32_bf16 v[90:93], v[142:145], v[198:201], v[90:93]
	v_mfma_f32_16x16x32_bf16 v[78:81], v[130:133], v[206:209], v[78:81]
	v_mfma_f32_16x16x32_bf16 v[74:77], v[142:145], v[206:209], v[74:77]
	s_setprio 0
	s_setprio 1
	v_mfma_f32_16x16x32_bf16 v[118:121], v[146:149], v[172:175], v[118:121]
	v_mfma_f32_16x16x32_bf16 v[114:117], v[154:157], v[172:175], v[114:117]
	v_mfma_f32_16x16x32_bf16 v[102:105], v[146:149], v[180:183], v[102:105]
	v_mfma_f32_16x16x32_bf16 v[98:101], v[154:157], v[180:183], v[98:101]
	v_mfma_f32_16x16x32_bf16 v[86:89], v[146:149], v[194:197], v[86:89]
	v_mfma_f32_16x16x32_bf16 v[82:85], v[154:157], v[194:197], v[82:85]
	v_mfma_f32_16x16x32_bf16 v[70:73], v[146:149], v[202:205], v[70:73]
	v_mfma_f32_16x16x32_bf16 v[66:69], v[154:157], v[202:205], v[66:69]
	v_mfma_f32_16x16x32_bf16 v[118:121], v[150:153], v[176:179], v[118:121]
	v_mfma_f32_16x16x32_bf16 v[114:117], v[168:171], v[176:179], v[114:117]
	v_mfma_f32_16x16x32_bf16 v[102:105], v[150:153], v[190:193], v[102:105]
	v_mfma_f32_16x16x32_bf16 v[98:101], v[168:171], v[190:193], v[98:101]
	v_mfma_f32_16x16x32_bf16 v[86:89], v[150:153], v[198:201], v[86:89]
	v_mfma_f32_16x16x32_bf16 v[82:85], v[168:171], v[198:201], v[82:85]
	v_mfma_f32_16x16x32_bf16 v[70:73], v[150:153], v[206:209], v[70:73]
	v_mfma_f32_16x16x32_bf16 v[66:69], v[168:171], v[206:209], v[66:69]
	s_barrier
; #define PG8_STAGE(bufoff, gbase, voff) do { _Pragma("unroll") for (int _i = 0; _i < 2; ++_i) \
;         __builtin_amdgcn_global_load_lds((const unsigned*)((const char*)(gbase) + (voff)[_i]), (PG8_LAS unsigned*)(lds + (bufoff) + ldsw + _i * 8192), 16, 0, 0); } while (0)
; #define PG8_LDA(dst, b, h) do { _Pragma("unroll") for (int m = 0; m < 4; ++m) _Pragma("unroll") for (int k = 0; k < 2; ++k) dst[m][k] = *(const PG8_LAS bf16x8*)(lds + PG8_SA(b, h) + aoff + m * 2048 + k * 1024); } while (0)
; #define PG8_MMA(ai, bj, At, Bt) do { __builtin_amdgcn_s_setprio(1); _Pragma("unroll") for (int m = 0; m < 4; ++m) _Pragma("unroll") for (int n = 0; n < 2; ++n) _Pragma("unroll") for (int k = 0; k < 2; ++k) \
;         acc[ai][bj][m][n] = __builtin_amdgcn_mfma_f32_16x16x32_bf16(Bt[n][k], At[m][k], acc[ai][bj][m][n], 0, 0, 0); __builtin_amdgcn_s_setprio(0); } while (0)
; #define PG8_WAIT_V(n) asm volatile("s_waitcnt vmcnt(" #n ")" ::: "memory")
; #define PG8_WAIT_L(n) asm volatile("s_waitcnt lgkmcnt(" #n ")" ::: "memory")
; #define PG8_BAR __builtin_amdgcn_s_barrier()
; #define PG8_SCHED __builtin_amdgcn_sched_barrier(0)
; template <class Epi, class Sched, bool ALIGN_EPI = false, bool SP2 = false>
; __device__ __forceinline__ void gemm_phase(PG8_LAS unsigned char* lds, const Gemm g, const Sched& S, const Epi& E, const int wv) {
;     ...
;             PG8_LDA(At, 1, 1); PG8_STAGE(PG8_SB(1, 0), b3, voffB); PG8_STAGE(PG8_SB(1, 1), b3 + hstep, voffB); PG8_STAGE(PG8_SA(1, 0), a3, voffA);
;             PG8_WAIT_V(8); PG8_WAIT_L(0); PG8_BAR; PG8_MMA(1, 0, At, B0); PG8_MMA(1, 1, At, B1); PG8_BAR; PG8_SCHED;
	s_setprio 0
	ds_read_b128 v[172:175], v189 offset:49152
	ds_read_b128 v[176:179], v189 offset:50176
	ds_read_b128 v[180:183], v189 offset:51200
	ds_read_b128 v[190:193], v189 offset:52224
	ds_read_b128 v[194:197], v189 offset:53248
	ds_read_b128 v[198:201], v189 offset:54272
	ds_read_b128 v[202:205], v189 offset:55296
	ds_read_b128 v[206:209], v189 offset:56320
	s_add_i32 s8, s52, s36
	v_lshl_add_u64 v[184:185], v[184:185], 0, s[2:3]
	s_mov_b32 m0, s8
	global_load_lds_dwordx4 v[184:185], off
	s_add_i32 m0, s8, 0x2000
	s_add_u32 s8, s26, 0xb0080
	v_lshl_add_u64 v[184:185], v[210:211], 0, s[2:3]
	s_addc_u32 s9, s27, 0
	s_add_i32 s26, s53, s36
	global_load_lds_dwordx4 v[184:185], off
	v_lshl_add_u64 v[184:185], s[8:9], 0, v[0:1]
	s_mov_b32 m0, s26
	s_nop 0
	global_load_lds_dwordx4 v[184:185], off
	v_lshl_add_u64 v[184:185], s[8:9], 0, v[162:163]
	s_add_i32 m0, s26, 0x2000
	s_nop 0
	global_load_lds_dwordx4 v[184:185], off
	v_lshl_add_u64 v[184:185], v[212:213], 0, s[2:3]
	s_mov_b32 m0, s42
	s_nop 0
	global_load_lds_dwordx4 v[184:185], off
	v_lshl_add_u64 v[184:185], v[214:215], 0, s[2:3]
	s_mov_b32 m0, s43
	s_nop 0
	global_load_lds_dwordx4 v[184:185], off
	s_waitcnt vmcnt(8)
	s_waitcnt lgkmcnt(0)
	s_setprio 1
	s_barrier
	s_waitcnt lgkmcnt(0)
	v_mfma_f32_16x16x32_bf16 v[62:65], v[122:125], v[172:175], v[62:65]
	v_mfma_f32_16x16x32_bf16 v[58:61], v[138:141], v[172:175], v[58:61]
	v_mfma_f32_16x16x32_bf16 v[46:49], v[122:125], v[180:183], v[46:49]
	v_mfma_f32_16x16x32_bf16 v[42:45], v[138:141], v[180:183], v[42:45]
	v_mfma_f32_16x16x32_bf16 v[30:33], v[122:125], v[194:197], v[30:33]
	v_mfma_f32_16x16x32_bf16 v[26:29], v[138:141], v[194:197], v[26:29]
	v_mfma_f32_16x16x32_bf16 v[14:17], v[122:125], v[202:205], v[14:17]
	v_mfma_f32_16x16x32_bf16 v[10:13], v[138:141], v[202:205], v[10:13]
	v_mfma_f32_16x16x32_bf16 v[62:65], v[130:133], v[176:179], v[62:65]
	v_mfma_f32_16x16x32_bf16 v[58:61], v[142:145], v[176:179], v[58:61]
	v_mfma_f32_16x16x32_bf16 v[46:49], v[130:133], v[190:193], v[46:49]
	v_mfma_f32_16x16x32_bf16 v[42:45], v[142:145], v[190:193], v[42:45]
	v_mfma_f32_16x16x32_bf16 v[30:33], v[130:133], v[198:201], v[30:33]
	v_mfma_f32_16x16x32_bf16 v[26:29], v[142:145], v[198:201], v[26:29]
	v_mfma_f32_16x16x32_bf16 v[14:17], v[130:133], v[206:209], v[14:17]
	v_mfma_f32_16x16x32_bf16 v[10:13], v[142:145], v[206:209], v[10:13]
	s_setprio 0
	s_setprio 1
	v_mfma_f32_16x16x32_bf16 v[54:57], v[146:149], v[172:175], v[54:57]
	v_mfma_f32_16x16x32_bf16 v[50:53], v[154:157], v[172:175], v[50:53]
	v_mfma_f32_16x16x32_bf16 v[38:41], v[146:149], v[180:183], v[38:41]
	v_mfma_f32_16x16x32_bf16 v[34:37], v[154:157], v[180:183], v[34:37]
	v_mfma_f32_16x16x32_bf16 v[22:25], v[146:149], v[194:197], v[22:25]
	v_mfma_f32_16x16x32_bf16 v[18:21], v[154:157], v[194:197], v[18:21]
	v_mfma_f32_16x16x32_bf16 v[6:9], v[146:149], v[202:205], v[6:9]
	v_mfma_f32_16x16x32_bf16 v[2:5], v[154:157], v[202:205], v[2:5]
	v_mfma_f32_16x16x32_bf16 v[54:57], v[150:153], v[176:179], v[54:57]
	v_mfma_f32_16x16x32_bf16 v[50:53], v[168:171], v[176:179], v[50:53]
	v_mfma_f32_16x16x32_bf16 v[38:41], v[150:153], v[190:193], v[38:41]
	v_mfma_f32_16x16x32_bf16 v[34:37], v[168:171], v[190:193], v[34:37]
	v_mfma_f32_16x16x32_bf16 v[22:25], v[150:153], v[198:201], v[22:25]
	v_mfma_f32_16x16x32_bf16 v[18:21], v[168:171], v[198:201], v[18:21]
	v_mfma_f32_16x16x32_bf16 v[6:9], v[150:153], v[206:209], v[6:9]
	v_mfma_f32_16x16x32_bf16 v[2:5], v[168:171], v[206:209], v[2:5]
	s_barrier
	s_setprio 0
	s_add_i32 s51, s51, 2
	s_add_u32 s49, s49, 0x100
	s_addc_u32 s50, s50, 0
	s_cmp_gt_u32 s51, 41
	s_mov_b64 s[8:9], s[10:11]
	s_cbranch_scc0 .LBB0_504
	s_and_b64 vcc, exec, s[18:19]
	s_cbranch_vccz .LBB0_507
	s_barrier
